# indexer top-k: sign-bit shift-register counting (v_sub+v_alignbit), per-group-count specialised threshold loops with scalar state, writelane mask build; setprio in attention/GEMM loops
# speedup vs baseline: 1.2060x; 1.0262x over previous
.LBB0_203:
	s_cmp_lt_i32 s24, 0
	s_cbranch_scc1 .LBB0_219
	s_lshr_b32 s4, s24, 3
	s_mul_hi_u32 s4, s4, 0x97b425f
	s_mul_i32 s5, s4, 0xd8
	s_sub_i32 s8, s24, s5
	s_lshl_b32 s5, s37, 4
	s_lshl_b32 s4, s4, 3
	s_add_i32 s4, s4, s5
	s_and_b32 s5, s8, 7
	s_or_b32 s4, s4, s5
	s_lshl_b32 s48, s4, 7
	s_lshl_b32 s4, s8, 4
	v_or_b32_e32 v100, s48, v214
	s_and_b32 s6, s4, 0xf80
	v_readfirstlane_b32 s4, v104
	s_and_b32 s49, s4, 64
	s_lshr_b32 s7, s4, 1
	s_and_b32 s50, s7, 0x7fffffc0
	s_lshr_b32 s7, s4, 6
	s_lshl_b32 s7, s7, 10
	v_bfe_u32 v217, v108, 1, 3
	v_lshlrev_b32_e32 v217, 4, v217
	v_xor_b32_e32 v217, v217, v110
	v_or_b32_e32 v218, s50, v108
	v_lshl_add_u32 v144, v218, 7, v217
	v_xor_b32_e32 v218, 64, v144
	v_or_b32_e32 v219, s49, v108
	v_lshl_add_u32 v100, v219, 7, v217
	v_xor_b32_e32 v219, 64, v100
	v_bfe_u32 v64, v214, 1, 3
	v_xor_b32_e32 v64, v64, v102
	v_lshlrev_b32_e32 v64, 4, v64
	v_lshl_add_u32 v64, v214, 11, v64
	v_add_u32_e32 v65, 0x10000, v64
	v_add_u32_e32 v66, 0x20000, v64
	v_add_u32_e32 v67, 0x30000, v64
	s_lshl_b32 s12, s48, 11
	s_add_u32 s4, s90, s12
	s_addc_u32 s5, s91, 0
	s_lshl_b32 s12, s6, 11
	s_add_u32 s24, s92, s12
	s_addc_u32 s25, s93, 0
	s_add_u32 m0, s7, 0x0
	s_nop 0
	global_load_lds_dwordx4 v64, s[4:5]
	s_add_u32 m0, s7, 0x1000
	s_nop 0
	global_load_lds_dwordx4 v65, s[4:5]
	s_add_u32 m0, s7, 0x2000
	s_nop 0
	global_load_lds_dwordx4 v66, s[4:5]
	s_add_u32 m0, s7, 0x3000
	s_nop 0
	global_load_lds_dwordx4 v67, s[4:5]
	s_add_u32 m0, s7, 0x9000
	s_nop 0
	global_load_lds_dwordx4 v64, s[24:25]
	s_add_u32 m0, s7, 0xa000
	s_nop 0
	global_load_lds_dwordx4 v65, s[24:25]
	s_add_u32 m0, s7, 0xb000
	s_nop 0
	global_load_lds_dwordx4 v66, s[24:25]
	s_add_u32 m0, s7, 0xc000
	s_nop 0
	global_load_lds_dwordx4 v67, s[24:25]
	s_add_u32 s4, s4, 0x80
	s_addc_u32 s5, s5, 0
	s_add_u32 s24, s24, 0x80
	s_addc_u32 s25, s25, 0
	v_mov_b64_e32 v[0:1], 0
	v_mov_b64_e32 v[2:3], 0
	v_mov_b64_e32 v[4:5], 0
	v_mov_b64_e32 v[6:7], 0
	v_mov_b64_e32 v[8:9], 0
	v_mov_b64_e32 v[10:11], 0
	v_mov_b64_e32 v[12:13], 0
	v_mov_b64_e32 v[14:15], 0
	v_mov_b64_e32 v[16:17], 0
	v_mov_b64_e32 v[18:19], 0
	v_mov_b64_e32 v[20:21], 0
	v_mov_b64_e32 v[22:23], 0
	v_mov_b64_e32 v[24:25], 0
	v_mov_b64_e32 v[26:27], 0
	v_mov_b64_e32 v[28:29], 0
	v_mov_b64_e32 v[30:31], 0
	v_mov_b64_e32 v[32:33], 0
	v_mov_b64_e32 v[34:35], 0
	v_mov_b64_e32 v[36:37], 0
	v_mov_b64_e32 v[38:39], 0
	v_mov_b64_e32 v[40:41], 0
	v_mov_b64_e32 v[42:43], 0
	v_mov_b64_e32 v[44:45], 0
	v_mov_b64_e32 v[46:47], 0
	v_mov_b64_e32 v[48:49], 0
	v_mov_b64_e32 v[50:51], 0
	v_mov_b64_e32 v[52:53], 0
	v_mov_b64_e32 v[54:55], 0
	v_mov_b64_e32 v[56:57], 0
	v_mov_b64_e32 v[58:59], 0
	v_mov_b64_e32 v[60:61], 0
	v_mov_b64_e32 v[62:63], 0
	s_mov_b32 s9, 0
	s_waitcnt vmcnt(0)
	s_barrier
	s_setprio 2

.Lg1_skip:
	ds_read_b128 v[68:71], v144 offset:18432
	ds_read_b128 v[84:87], v100 offset:55296
	ds_read_b128 v[88:91], v100 offset:57344
	ds_read_b128 v[92:95], v100 offset:59392
	ds_read_b128 v[158:161], v100 offset:61440
	ds_read_b128 v[72:75], v144 offset:20480
	ds_read_b128 v[76:79], v144 offset:22528
	ds_read_b128 v[80:83], v144 offset:24576
	s_waitcnt lgkmcnt(6)
	v_mfma_f32_16x16x32_bf16 v[44:47], v[68:71], v[84:87], v[44:47]
	ds_read_b128 v[162:165], v218 offset:18432
	ds_read_b128 v[178:181], v219 offset:55296
	s_waitcnt lgkmcnt(7)
	v_mfma_f32_16x16x32_bf16 v[52:55], v[68:71], v[88:91], v[52:55]
	ds_read_b128 v[182:185], v219 offset:57344
	ds_read_b128 v[186:189], v219 offset:59392
	s_waitcnt lgkmcnt(8)
	v_mfma_f32_16x16x32_bf16 v[60:63], v[68:71], v[92:95], v[60:63]
	ds_read_b128 v[190:193], v219 offset:61440
	ds_read_b128 v[166:169], v218 offset:20480
	s_waitcnt lgkmcnt(9)
	v_mfma_f32_16x16x32_bf16 v[56:59], v[68:71], v[158:161], v[56:59]
	ds_read_b128 v[170:173], v218 offset:22528
	s_waitcnt lgkmcnt(9)
	v_mfma_f32_16x16x32_bf16 v[40:43], v[72:75], v[84:87], v[40:43]
	v_mfma_f32_16x16x32_bf16 v[36:39], v[72:75], v[88:91], v[36:39]
	v_mfma_f32_16x16x32_bf16 v[32:35], v[72:75], v[92:95], v[32:35]
	v_mfma_f32_16x16x32_bf16 v[28:31], v[72:75], v[158:161], v[28:31]
	ds_read_b128 v[174:177], v218 offset:24576
	s_waitcnt lgkmcnt(9)
	v_mfma_f32_16x16x32_bf16 v[24:27], v[76:79], v[84:87], v[24:27]
	v_mfma_f32_16x16x32_bf16 v[20:23], v[76:79], v[88:91], v[20:23]
	v_mfma_f32_16x16x32_bf16 v[16:19], v[76:79], v[92:95], v[16:19]
	v_mfma_f32_16x16x32_bf16 v[12:15], v[76:79], v[158:161], v[12:15]
	s_waitcnt lgkmcnt(8)
	v_mfma_f32_16x16x32_bf16 v[8:11], v[80:83], v[84:87], v[8:11]
	v_mfma_f32_16x16x32_bf16 v[4:7], v[80:83], v[88:91], v[4:7]
	v_mfma_f32_16x16x32_bf16 v[0:3], v[80:83], v[92:95], v[0:3]
	v_mfma_f32_16x16x32_bf16 v[48:51], v[80:83], v[158:161], v[48:51]
	s_waitcnt lgkmcnt(6)
	v_mfma_f32_16x16x32_bf16 v[44:47], v[162:165], v[178:181], v[44:47]
	s_waitcnt lgkmcnt(5)
	v_mfma_f32_16x16x32_bf16 v[52:55], v[162:165], v[182:185], v[52:55]
	s_waitcnt lgkmcnt(4)
	v_mfma_f32_16x16x32_bf16 v[60:63], v[162:165], v[186:189], v[60:63]
	s_waitcnt lgkmcnt(3)
	v_mfma_f32_16x16x32_bf16 v[56:59], v[162:165], v[190:193], v[56:59]
	s_waitcnt lgkmcnt(2)
	v_mfma_f32_16x16x32_bf16 v[40:43], v[166:169], v[178:181], v[40:43]
	v_mfma_f32_16x16x32_bf16 v[36:39], v[166:169], v[182:185], v[36:39]
	v_mfma_f32_16x16x32_bf16 v[32:35], v[166:169], v[186:189], v[32:35]
	v_mfma_f32_16x16x32_bf16 v[28:31], v[166:169], v[190:193], v[28:31]
	s_waitcnt lgkmcnt(1)
	v_mfma_f32_16x16x32_bf16 v[24:27], v[170:173], v[178:181], v[24:27]
	v_mfma_f32_16x16x32_bf16 v[20:23], v[170:173], v[182:185], v[20:23]
	v_mfma_f32_16x16x32_bf16 v[16:19], v[170:173], v[186:189], v[16:19]
	v_mfma_f32_16x16x32_bf16 v[12:15], v[170:173], v[190:193], v[12:15]
	s_waitcnt lgkmcnt(0)
	v_mfma_f32_16x16x32_bf16 v[8:11], v[174:177], v[178:181], v[8:11]
	v_mfma_f32_16x16x32_bf16 v[4:7], v[174:177], v[182:185], v[4:7]
	v_mfma_f32_16x16x32_bf16 v[0:3], v[174:177], v[186:189], v[0:3]
	v_mfma_f32_16x16x32_bf16 v[48:51], v[174:177], v[190:193], v[48:51]
	s_waitcnt vmcnt(0)
	s_barrier
	s_add_i32 s9, s9, 1
	s_cmp_lg_u32 s9, 8
	s_cbranch_scc1 .Lg1_loop
	s_setprio 0
	s_or_b32 s52, s49, s6
	s_cmp_gt_u32 s8, 31
	s_mov_b64 s[4:5], -1
	s_cbranch_scc0 .LBB0_220
	s_cmp_lt_u32 s8, 48
	s_cbranch_scc1 .LBB0_221
	s_cmp_lt_u32 s8, 56
	s_cbranch_scc1 .LBB0_225
	s_cmp_lt_u32 s8, 64
	s_cbranch_scc1 .LBB0_233
	s_cmpk_lt_u32 s8, 0x48
	s_cbranch_scc1 .LBB0_546
	s_cmpk_lt_u32 s8, 0x50
	s_cbranch_scc1 .LBB0_547
	s_cmpk_lt_u32 s8, 0x70
	s_cbranch_scc1 .LBB0_548
	s_cmpk_lt_u32 s8, 0x90
	s_cbranch_scc1 .LBB0_549
	s_cmpk_lt_u32 s8, 0x98
	s_cbranch_scc1 .LBB0_550
	s_cmpk_lt_u32 s8, 0xa0
	s_mov_b64 s[6:7], 0
	s_cbranch_scc1 .LBB0_551
	s_cmpk_lt_u32 s8, 0xb0
	s_mov_b64 s[30:31], 0
	s_cbranch_scc1 .LBB0_552
	s_cmpk_eq_i32 s52, 0xb00
	s_cbranch_scc1 .LBB0_553
	s_cmpk_lt_u32 s52, 0xd40
	s_cselect_b64 s[8:9], -1, 0
	s_cmpk_gt_u32 s52, 0xd3f
	s_cselect_b64 s[28:29], -1, 0
	s_mov_b64 s[26:27], 0
	s_branch .LBB0_554

.LBB0_643:
	v_add_u32_e32 v44, -1, v44
	s_add_i32 s30, s29, s52
	s_lshl_b64 s[36:37], s[30:31], 9
	s_mov_b32 s29, 4
	s_movk_i32 s48, 0xfff
	v_lshl_add_u64 v[254:255], v[126:127], 0, s[36:37]
	v_cmp_lt_u32_e64 s[38:39], v44, v41
	v_cmp_lt_u32_e64 s[40:41], v44, v39
	v_cmp_lt_u32_e64 s[42:43], v44, v38
	v_writelane_b32 v252, s38, 0
	v_writelane_b32 v253, s39, 0
	v_cmp_lt_u32_e64 s[44:45], v44, v37
	v_writelane_b32 v252, s40, 1
	v_writelane_b32 v253, s41, 1
	v_cmp_lt_u32_e64 s[38:39], v44, v1
	v_writelane_b32 v252, s42, 2
	v_writelane_b32 v253, s43, 2
	v_cmp_lt_u32_e64 s[40:41], v44, v0
	v_writelane_b32 v252, s44, 3
	v_writelane_b32 v253, s45, 3
	v_cmp_lt_u32_e64 s[42:43], v44, v3
	v_writelane_b32 v252, s38, 4
	v_writelane_b32 v253, s39, 4
	v_cmp_lt_u32_e64 s[44:45], v44, v2
	v_writelane_b32 v252, s40, 5
	v_writelane_b32 v253, s41, 5
	v_cmp_lt_u32_e64 s[38:39], v44, v5
	v_writelane_b32 v252, s42, 6
	v_writelane_b32 v253, s43, 6
	v_cmp_lt_u32_e64 s[40:41], v44, v4
	v_writelane_b32 v252, s44, 7
	v_writelane_b32 v253, s45, 7
	v_cmp_lt_u32_e64 s[42:43], v44, v7
	v_writelane_b32 v252, s38, 8
	v_writelane_b32 v253, s39, 8
	v_cmp_lt_u32_e64 s[44:45], v44, v6
	v_writelane_b32 v252, s40, 9
	v_writelane_b32 v253, s41, 9
	v_cmp_lt_u32_e64 s[38:39], v44, v9
	v_writelane_b32 v252, s42, 10
	v_writelane_b32 v253, s43, 10
	v_cmp_lt_u32_e64 s[40:41], v44, v8
	v_writelane_b32 v252, s44, 11
	v_writelane_b32 v253, s45, 11
	v_cmp_lt_u32_e64 s[42:43], v44, v11
	v_writelane_b32 v252, s38, 12
	v_writelane_b32 v253, s39, 12
	v_cmp_lt_u32_e64 s[44:45], v44, v10
	v_writelane_b32 v252, s40, 13
	v_writelane_b32 v253, s41, 13
	v_cmp_lt_u32_e64 s[38:39], v44, v13
	v_writelane_b32 v252, s42, 14
	v_writelane_b32 v253, s43, 14
	v_cmp_lt_u32_e64 s[40:41], v44, v12
	v_writelane_b32 v252, s44, 15
	v_writelane_b32 v253, s45, 15
	v_cmp_lt_u32_e64 s[42:43], v44, v15
	v_writelane_b32 v252, s38, 16
	v_writelane_b32 v253, s39, 16
	v_cmp_lt_u32_e64 s[44:45], v44, v14
	v_writelane_b32 v252, s40, 17
	v_writelane_b32 v253, s41, 17
	v_cmp_lt_u32_e64 s[38:39], v44, v17
	v_writelane_b32 v252, s42, 18
	v_writelane_b32 v253, s43, 18
	v_cmp_lt_u32_e64 s[40:41], v44, v16
	v_writelane_b32 v252, s44, 19
	v_writelane_b32 v253, s45, 19
	v_cmp_lt_u32_e64 s[42:43], v44, v19
	v_writelane_b32 v252, s38, 20
	v_writelane_b32 v253, s39, 20
	v_cmp_lt_u32_e64 s[44:45], v44, v18
	v_writelane_b32 v252, s40, 21
	v_writelane_b32 v253, s41, 21
	v_cmp_lt_u32_e64 s[38:39], v44, v21
	v_writelane_b32 v252, s42, 22
	v_writelane_b32 v253, s43, 22
	v_cmp_lt_u32_e64 s[40:41], v44, v20
	v_writelane_b32 v252, s44, 23
	v_writelane_b32 v253, s45, 23
	v_cmp_lt_u32_e64 s[42:43], v44, v23
	v_writelane_b32 v252, s38, 24
	v_writelane_b32 v253, s39, 24
	v_cmp_lt_u32_e64 s[44:45], v44, v22
	v_writelane_b32 v252, s40, 25
	v_writelane_b32 v253, s41, 25
	v_cmp_lt_u32_e64 s[38:39], v44, v25
	v_writelane_b32 v252, s42, 26
	v_writelane_b32 v253, s43, 26
	v_cmp_lt_u32_e64 s[40:41], v44, v24
	v_writelane_b32 v252, s44, 27
	v_writelane_b32 v253, s45, 27
	v_cmp_lt_u32_e64 s[42:43], v44, v27
	v_writelane_b32 v252, s38, 28
	v_writelane_b32 v253, s39, 28
	v_cmp_lt_u32_e64 s[44:45], v44, v26
	v_writelane_b32 v252, s40, 29
	v_writelane_b32 v253, s41, 29
	v_cmp_lt_u32_e64 s[38:39], v44, v29
	v_writelane_b32 v252, s42, 30
	v_writelane_b32 v253, s43, 30
	v_cmp_lt_u32_e64 s[40:41], v44, v28
	v_writelane_b32 v252, s44, 31
	v_writelane_b32 v253, s45, 31
	v_cmp_lt_u32_e64 s[42:43], v44, v31
	v_writelane_b32 v252, s38, 32
	v_writelane_b32 v253, s39, 32
	v_cmp_lt_u32_e64 s[44:45], v44, v30
	v_writelane_b32 v252, s40, 33
	v_writelane_b32 v253, s41, 33
	v_cmp_lt_u32_e64 s[38:39], v44, v33
	v_writelane_b32 v252, s42, 34
	v_writelane_b32 v253, s43, 34
	v_cmp_lt_u32_e64 s[40:41], v44, v32
	v_writelane_b32 v252, s44, 35
	v_writelane_b32 v253, s45, 35
	v_cmp_lt_u32_e64 s[42:43], v44, v35
	v_writelane_b32 v252, s38, 36
	v_writelane_b32 v253, s39, 36
	v_cmp_lt_u32_e64 s[44:45], v44, v34
	v_writelane_b32 v252, s40, 37
	v_writelane_b32 v253, s41, 37
	v_cmp_lt_u32_e64 s[38:39], v44, v40
	v_writelane_b32 v252, s42, 38
	v_writelane_b32 v253, s43, 38
	v_cmp_lt_u32_e64 s[40:41], v44, v36
	v_writelane_b32 v252, s44, 39
	v_writelane_b32 v253, s45, 39
	v_cmp_lt_u32_e64 s[42:43], v44, v43
	v_writelane_b32 v252, s38, 40
	v_writelane_b32 v253, s39, 40
	v_cmp_lt_u32_e64 s[44:45], v44, v42
	v_writelane_b32 v252, s40, 41
	v_writelane_b32 v253, s41, 41
	v_cmp_lt_u32_e64 s[38:39], v44, v46
	v_writelane_b32 v252, s42, 42
	v_writelane_b32 v253, s43, 42
	v_cmp_lt_u32_e64 s[40:41], v44, v45
	v_writelane_b32 v252, s44, 43
	v_writelane_b32 v253, s45, 43
	v_cmp_lt_u32_e64 s[42:43], v44, v48
	v_writelane_b32 v252, s38, 44
	v_writelane_b32 v253, s39, 44
	v_cmp_lt_u32_e64 s[44:45], v44, v47
	v_writelane_b32 v252, s40, 45
	v_writelane_b32 v253, s41, 45
	v_cmp_lt_u32_e64 s[38:39], v44, v50
	v_writelane_b32 v252, s42, 46
	v_writelane_b32 v253, s43, 46
	v_cmp_lt_u32_e64 s[40:41], v44, v49
	v_writelane_b32 v252, s44, 47
	v_writelane_b32 v253, s45, 47
	v_cmp_lt_u32_e64 s[42:43], v44, v52
	v_writelane_b32 v252, s38, 48
	v_writelane_b32 v253, s39, 48
	v_cmp_lt_u32_e64 s[44:45], v44, v51
	v_writelane_b32 v252, s40, 49
	v_writelane_b32 v253, s41, 49
	v_cmp_lt_u32_e64 s[38:39], v44, v54
	v_writelane_b32 v252, s42, 50
	v_writelane_b32 v253, s43, 50
	v_cmp_lt_u32_e64 s[40:41], v44, v53
	v_writelane_b32 v252, s44, 51
	v_writelane_b32 v253, s45, 51
	v_cmp_lt_u32_e64 s[42:43], v44, v56
	v_writelane_b32 v252, s38, 52
	v_writelane_b32 v253, s39, 52
	v_cmp_lt_u32_e64 s[44:45], v44, v55
	v_writelane_b32 v252, s40, 53
	v_writelane_b32 v253, s41, 53
	v_cmp_lt_u32_e64 s[38:39], v44, v58
	v_writelane_b32 v252, s42, 54
	v_writelane_b32 v253, s43, 54
	v_cmp_lt_u32_e64 s[40:41], v44, v57
	v_writelane_b32 v252, s44, 55
	v_writelane_b32 v253, s45, 55
	v_cmp_lt_u32_e64 s[42:43], v44, v60
	v_writelane_b32 v252, s38, 56
	v_writelane_b32 v253, s39, 56
	v_cmp_lt_u32_e64 s[44:45], v44, v59
	v_writelane_b32 v252, s40, 57
	v_writelane_b32 v253, s41, 57
	v_cmp_lt_u32_e64 s[38:39], v44, v62
	v_writelane_b32 v252, s42, 58
	v_writelane_b32 v253, s43, 58
	v_cmp_lt_u32_e64 s[40:41], v44, v61
	v_writelane_b32 v252, s44, 59
	v_writelane_b32 v253, s45, 59
	v_cmp_lt_u32_e64 s[42:43], v44, v64
	v_writelane_b32 v252, s38, 60
	v_writelane_b32 v253, s39, 60
	v_cmp_lt_u32_e64 s[44:45], v44, v63
	v_writelane_b32 v252, s40, 61
	v_writelane_b32 v253, s41, 61
	s_nop 0
	v_writelane_b32 v252, s42, 62
	v_writelane_b32 v253, s43, 62
	s_nop 0
	v_writelane_b32 v252, s44, 63
	v_writelane_b32 v253, s45, 63
	s_and_b64 vcc, exec, s[34:35]
	s_mov_b64 s[34:35], 0
	global_store_dwordx2 v[254:255], v[252:253], off sc1
	s_cbranch_vccnz .LBB0_780

.LBB0_764:
	s_or_b64 exec, exec, s[36:37]
	s_xor_b64 s[34:35], s[34:35], -1
	s_cmpk_gt_u32 s29, 0x1ff
	s_cselect_b64 s[36:37], -1, 0
	s_cmpk_gt_u32 s29, 0x3ff
	s_cselect_b64 s[38:39], -1, 0
	s_cmpk_gt_u32 s29, 0x5ff
	s_cselect_b64 s[40:41], -1, 0
	s_cmpk_gt_u32 s29, 0x7ff
	s_waitcnt lgkmcnt(2)
	v_lshlrev_b32_sdwa v39, v223, v39 dst_sel:DWORD dst_unused:UNUSED_PAD src0_sel:DWORD src1_sel:WORD_0
	s_movk_i32 s30, 0xfbf
	s_cselect_b64 s[42:43], -1, 0
	s_cmpk_gt_u32 s29, 0x9ff
	v_bitop3_b32 v39, v39, s30, v106 bitop3:0x36
	s_waitcnt lgkmcnt(1)
	v_lshlrev_b32_sdwa v38, v223, v38 dst_sel:DWORD dst_unused:UNUSED_PAD src0_sel:DWORD src1_sel:WORD_0
	s_movk_i32 s30, 0xf7f
	s_cselect_b64 s[44:45], -1, 0
	s_cmpk_gt_u32 s29, 0xbff
	v_lshlrev_b32_sdwa v41, v223, v41 dst_sel:DWORD dst_unused:UNUSED_PAD src0_sel:DWORD src1_sel:WORD_0
	v_bitop3_b32 v38, v38, s30, v106 bitop3:0x36
	s_waitcnt lgkmcnt(0)
	v_lshlrev_b32_sdwa v37, v223, v37 dst_sel:DWORD dst_unused:UNUSED_PAD src0_sel:DWORD src1_sel:WORD_0
	s_movk_i32 s30, 0xf3f
	s_cselect_b64 s[46:47], -1, 0
	s_cmpk_gt_u32 s29, 0xdff
	v_bitop3_b32 v41, v41, s48, v106 bitop3:0x36
	v_bitop3_b32 v37, v37, s30, v106 bitop3:0x36
	s_cselect_b64 s[48:49], -1, 0
	s_lshr_b32 s57, s29, 9
	s_mov_b32 s58, 0
	s_mov_b32 s59, 27
	s_mov_b32 s60, 0x8000000
	v_mov_b32_e32 v254, 0
	v_mov_b32_e32 v255, 0
	s_cmp_eq_u32 s57, 0
	s_cbranch_scc1 .Lbq1_loop
	s_cmp_eq_u32 s57, 1
	s_cbranch_scc1 .Lbq2_loop
	s_cmp_eq_u32 s57, 2
	s_cbranch_scc1 .Lbq3_loop
	s_cmp_eq_u32 s57, 3
	s_cbranch_scc1 .Lbq4_loop
	s_cmp_eq_u32 s57, 4
	s_cbranch_scc1 .Lbq5_loop
	s_cmp_eq_u32 s57, 5
	s_cbranch_scc1 .Lbq6_loop
	s_cmp_eq_u32 s57, 6
	s_cbranch_scc1 .Lbq7_loop
.Lbq8_loop:
	v_subrev_u32_e32 v252, s60, v41
	v_subrev_u32_e32 v253, s60, v39
	v_alignbit_b32 v254, v254, v252, 31
	v_alignbit_b32 v255, v255, v253, 31
	v_subrev_u32_e32 v252, s60, v38
	v_subrev_u32_e32 v253, s60, v37
	v_alignbit_b32 v254, v254, v252, 31
	v_alignbit_b32 v255, v255, v253, 31
	v_subrev_u32_e32 v252, s60, v1
	v_subrev_u32_e32 v253, s60, v0
	v_alignbit_b32 v254, v254, v252, 31
	v_alignbit_b32 v255, v255, v253, 31
	v_subrev_u32_e32 v252, s60, v3
	v_subrev_u32_e32 v253, s60, v2
	v_alignbit_b32 v254, v254, v252, 31
	v_alignbit_b32 v255, v255, v253, 31
	v_subrev_u32_e32 v252, s60, v5
	v_subrev_u32_e32 v253, s60, v4
	v_alignbit_b32 v254, v254, v252, 31
	v_alignbit_b32 v255, v255, v253, 31
	v_subrev_u32_e32 v252, s60, v7
	v_subrev_u32_e32 v253, s60, v6
	v_alignbit_b32 v254, v254, v252, 31
	v_alignbit_b32 v255, v255, v253, 31
	v_subrev_u32_e32 v252, s60, v9
	v_subrev_u32_e32 v253, s60, v8
	v_alignbit_b32 v254, v254, v252, 31
	v_alignbit_b32 v255, v255, v253, 31
	v_subrev_u32_e32 v252, s60, v11
	v_subrev_u32_e32 v253, s60, v10
	v_alignbit_b32 v254, v254, v252, 31
	v_alignbit_b32 v255, v255, v253, 31
	v_subrev_u32_e32 v252, s60, v13
	v_subrev_u32_e32 v253, s60, v12
	v_alignbit_b32 v254, v254, v252, 31
	v_alignbit_b32 v255, v255, v253, 31
	v_subrev_u32_e32 v252, s60, v15
	v_subrev_u32_e32 v253, s60, v14
	v_alignbit_b32 v254, v254, v252, 31
	v_alignbit_b32 v255, v255, v253, 31
	v_subrev_u32_e32 v252, s60, v17
	v_subrev_u32_e32 v253, s60, v16
	v_alignbit_b32 v254, v254, v252, 31
	v_alignbit_b32 v255, v255, v253, 31
	v_subrev_u32_e32 v252, s60, v19
	v_subrev_u32_e32 v253, s60, v18
	v_alignbit_b32 v254, v254, v252, 31
	v_alignbit_b32 v255, v255, v253, 31
	v_subrev_u32_e32 v252, s60, v21
	v_subrev_u32_e32 v253, s60, v20
	v_alignbit_b32 v254, v254, v252, 31
	v_alignbit_b32 v255, v255, v253, 31
	v_subrev_u32_e32 v252, s60, v23
	v_subrev_u32_e32 v253, s60, v22
	v_alignbit_b32 v254, v254, v252, 31
	v_alignbit_b32 v255, v255, v253, 31
	v_subrev_u32_e32 v252, s60, v25
	v_subrev_u32_e32 v253, s60, v24
	v_alignbit_b32 v254, v254, v252, 31
	v_alignbit_b32 v255, v255, v253, 31
	v_subrev_u32_e32 v252, s60, v27
	v_subrev_u32_e32 v253, s60, v26
	v_alignbit_b32 v254, v254, v252, 31
	v_alignbit_b32 v255, v255, v253, 31
	v_subrev_u32_e32 v252, s60, v29
	v_subrev_u32_e32 v253, s60, v28
	v_alignbit_b32 v254, v254, v252, 31
	v_alignbit_b32 v255, v255, v253, 31
	v_subrev_u32_e32 v252, s60, v31
	v_subrev_u32_e32 v253, s60, v30
	v_alignbit_b32 v254, v254, v252, 31
	v_alignbit_b32 v255, v255, v253, 31
	v_subrev_u32_e32 v252, s60, v33
	v_subrev_u32_e32 v253, s60, v32
	v_alignbit_b32 v254, v254, v252, 31
	v_alignbit_b32 v255, v255, v253, 31
	v_subrev_u32_e32 v252, s60, v35
	v_subrev_u32_e32 v253, s60, v34
	v_alignbit_b32 v254, v254, v252, 31
	v_alignbit_b32 v255, v255, v253, 31
	v_subrev_u32_e32 v252, s60, v40
	v_subrev_u32_e32 v253, s60, v36
	v_alignbit_b32 v254, v254, v252, 31
	v_alignbit_b32 v255, v255, v253, 31
	v_subrev_u32_e32 v252, s60, v43
	v_subrev_u32_e32 v253, s60, v42
	v_alignbit_b32 v254, v254, v252, 31
	v_alignbit_b32 v255, v255, v253, 31
	v_subrev_u32_e32 v252, s60, v46
	v_subrev_u32_e32 v253, s60, v45
	v_alignbit_b32 v254, v254, v252, 31
	v_alignbit_b32 v255, v255, v253, 31
	v_subrev_u32_e32 v252, s60, v48
	v_subrev_u32_e32 v253, s60, v47
	v_alignbit_b32 v254, v254, v252, 31
	v_alignbit_b32 v255, v255, v253, 31
	v_subrev_u32_e32 v252, s60, v50
	v_subrev_u32_e32 v253, s60, v49
	v_alignbit_b32 v254, v254, v252, 31
	v_alignbit_b32 v255, v255, v253, 31
	v_subrev_u32_e32 v252, s60, v52
	v_subrev_u32_e32 v253, s60, v51
	v_alignbit_b32 v254, v254, v252, 31
	v_alignbit_b32 v255, v255, v253, 31
	v_subrev_u32_e32 v252, s60, v54
	v_subrev_u32_e32 v253, s60, v53
	v_alignbit_b32 v254, v254, v252, 31
	v_alignbit_b32 v255, v255, v253, 31
	v_subrev_u32_e32 v252, s60, v56
	v_subrev_u32_e32 v253, s60, v55
	v_alignbit_b32 v254, v254, v252, 31
	v_alignbit_b32 v255, v255, v253, 31
	v_subrev_u32_e32 v252, s60, v58
	v_subrev_u32_e32 v253, s60, v57
	v_alignbit_b32 v254, v254, v252, 31
	v_alignbit_b32 v255, v255, v253, 31
	v_subrev_u32_e32 v252, s60, v60
	v_subrev_u32_e32 v253, s60, v59
	v_alignbit_b32 v254, v254, v252, 31
	v_alignbit_b32 v255, v255, v253, 31
	v_subrev_u32_e32 v252, s60, v62
	v_subrev_u32_e32 v253, s60, v61
	v_alignbit_b32 v254, v254, v252, 31
	v_alignbit_b32 v255, v255, v253, 31
	v_subrev_u32_e32 v252, s60, v64
	v_subrev_u32_e32 v253, s60, v63
	v_alignbit_b32 v254, v254, v252, 31
	v_alignbit_b32 v255, v255, v253, 31
	v_bcnt_u32_b32 v251, v254, 0
	v_bcnt_u32_b32 v251, v255, v251
	s_nop 1
	v_add_u32_dpp v251, v251, v251 quad_perm:[1,0,3,2] row_mask:0xf bank_mask:0xf
	v_mov_b32_e32 v254, 0
	v_mov_b32_e32 v255, 0
	v_add_u32_dpp v251, v251, v251 quad_perm:[2,3,0,1] row_mask:0xf bank_mask:0xf
	s_nop 1
	v_add_u32_dpp v251, v251, v251 row_half_mirror row_mask:0xf bank_mask:0xf
	s_nop 1
	v_add_u32_dpp v251, v251, v251 row_mirror row_mask:0xf bank_mask:0xf
	s_nop 1
	v_readlane_b32 s30, v251, 0
	v_readlane_b32 s54, v251, 16
	v_readlane_b32 s55, v251, 32
	v_readlane_b32 s56, v251, 48
	s_add_i32 s30, s30, s54
	s_add_i32 s55, s55, s56
	s_add_i32 s30, s30, s55
	s_sub_i32 s30, 0x1000, s30
	s_cmpk_lt_u32 s30, 0x100
	s_cselect_b32 s58, s58, s60
	s_cmpk_eq_i32 s30, 0x100
	s_cbranch_scc1 .Lbq_exit
	s_sub_u32 s59, s59, 1
	s_cbranch_scc1 .Lbq_exit
	s_lshl_b32 s60, 1, s59
	s_or_b32 s60, s60, s58
	s_branch .Lbq8_loop
.Lbq7_loop:
	v_subrev_u32_e32 v252, s60, v41
	v_subrev_u32_e32 v253, s60, v39
	v_alignbit_b32 v254, v254, v252, 31
	v_alignbit_b32 v255, v255, v253, 31
	v_subrev_u32_e32 v252, s60, v38
	v_subrev_u32_e32 v253, s60, v37
	v_alignbit_b32 v254, v254, v252, 31
	v_alignbit_b32 v255, v255, v253, 31
	v_subrev_u32_e32 v252, s60, v1
	v_subrev_u32_e32 v253, s60, v0
	v_alignbit_b32 v254, v254, v252, 31
	v_alignbit_b32 v255, v255, v253, 31
	v_subrev_u32_e32 v252, s60, v3
	v_subrev_u32_e32 v253, s60, v2
	v_alignbit_b32 v254, v254, v252, 31
	v_alignbit_b32 v255, v255, v253, 31
	v_subrev_u32_e32 v252, s60, v5
	v_subrev_u32_e32 v253, s60, v4
	v_alignbit_b32 v254, v254, v252, 31
	v_alignbit_b32 v255, v255, v253, 31
	v_subrev_u32_e32 v252, s60, v7
	v_subrev_u32_e32 v253, s60, v6
	v_alignbit_b32 v254, v254, v252, 31
	v_alignbit_b32 v255, v255, v253, 31
	v_subrev_u32_e32 v252, s60, v9
	v_subrev_u32_e32 v253, s60, v8
	v_alignbit_b32 v254, v254, v252, 31
	v_alignbit_b32 v255, v255, v253, 31
	v_subrev_u32_e32 v252, s60, v11
	v_subrev_u32_e32 v253, s60, v10
	v_alignbit_b32 v254, v254, v252, 31
	v_alignbit_b32 v255, v255, v253, 31
	v_subrev_u32_e32 v252, s60, v13
	v_subrev_u32_e32 v253, s60, v12
	v_alignbit_b32 v254, v254, v252, 31
	v_alignbit_b32 v255, v255, v253, 31
	v_subrev_u32_e32 v252, s60, v15
	v_subrev_u32_e32 v253, s60, v14
	v_alignbit_b32 v254, v254, v252, 31
	v_alignbit_b32 v255, v255, v253, 31
	v_subrev_u32_e32 v252, s60, v17
	v_subrev_u32_e32 v253, s60, v16
	v_alignbit_b32 v254, v254, v252, 31
	v_alignbit_b32 v255, v255, v253, 31
	v_subrev_u32_e32 v252, s60, v19
	v_subrev_u32_e32 v253, s60, v18
	v_alignbit_b32 v254, v254, v252, 31
	v_alignbit_b32 v255, v255, v253, 31
	v_subrev_u32_e32 v252, s60, v21
	v_subrev_u32_e32 v253, s60, v20
	v_alignbit_b32 v254, v254, v252, 31
	v_alignbit_b32 v255, v255, v253, 31
	v_subrev_u32_e32 v252, s60, v23
	v_subrev_u32_e32 v253, s60, v22
	v_alignbit_b32 v254, v254, v252, 31
	v_alignbit_b32 v255, v255, v253, 31
	v_subrev_u32_e32 v252, s60, v25
	v_subrev_u32_e32 v253, s60, v24
	v_alignbit_b32 v254, v254, v252, 31
	v_alignbit_b32 v255, v255, v253, 31
	v_subrev_u32_e32 v252, s60, v27
	v_subrev_u32_e32 v253, s60, v26
	v_alignbit_b32 v254, v254, v252, 31
	v_alignbit_b32 v255, v255, v253, 31
	v_subrev_u32_e32 v252, s60, v29
	v_subrev_u32_e32 v253, s60, v28
	v_alignbit_b32 v254, v254, v252, 31
	v_alignbit_b32 v255, v255, v253, 31
	v_subrev_u32_e32 v252, s60, v31
	v_subrev_u32_e32 v253, s60, v30
	v_alignbit_b32 v254, v254, v252, 31
	v_alignbit_b32 v255, v255, v253, 31
	v_subrev_u32_e32 v252, s60, v33
	v_subrev_u32_e32 v253, s60, v32
	v_alignbit_b32 v254, v254, v252, 31
	v_alignbit_b32 v255, v255, v253, 31
	v_subrev_u32_e32 v252, s60, v35
	v_subrev_u32_e32 v253, s60, v34
	v_alignbit_b32 v254, v254, v252, 31
	v_alignbit_b32 v255, v255, v253, 31
	v_subrev_u32_e32 v252, s60, v40
	v_subrev_u32_e32 v253, s60, v36
	v_alignbit_b32 v254, v254, v252, 31
	v_alignbit_b32 v255, v255, v253, 31
	v_subrev_u32_e32 v252, s60, v43
	v_subrev_u32_e32 v253, s60, v42
	v_alignbit_b32 v254, v254, v252, 31
	v_alignbit_b32 v255, v255, v253, 31
	v_subrev_u32_e32 v252, s60, v46
	v_subrev_u32_e32 v253, s60, v45
	v_alignbit_b32 v254, v254, v252, 31
	v_alignbit_b32 v255, v255, v253, 31
	v_subrev_u32_e32 v252, s60, v48
	v_subrev_u32_e32 v253, s60, v47
	v_alignbit_b32 v254, v254, v252, 31
	v_alignbit_b32 v255, v255, v253, 31
	v_subrev_u32_e32 v252, s60, v50
	v_subrev_u32_e32 v253, s60, v49
	v_alignbit_b32 v254, v254, v252, 31
	v_alignbit_b32 v255, v255, v253, 31
	v_subrev_u32_e32 v252, s60, v52
	v_subrev_u32_e32 v253, s60, v51
	v_alignbit_b32 v254, v254, v252, 31
	v_alignbit_b32 v255, v255, v253, 31
	v_subrev_u32_e32 v252, s60, v54
	v_subrev_u32_e32 v253, s60, v53
	v_alignbit_b32 v254, v254, v252, 31
	v_alignbit_b32 v255, v255, v253, 31
	v_subrev_u32_e32 v252, s60, v56
	v_subrev_u32_e32 v253, s60, v55
	v_alignbit_b32 v254, v254, v252, 31
	v_alignbit_b32 v255, v255, v253, 31
	v_bcnt_u32_b32 v251, v254, 0
	v_bcnt_u32_b32 v251, v255, v251
	s_nop 1
	v_add_u32_dpp v251, v251, v251 quad_perm:[1,0,3,2] row_mask:0xf bank_mask:0xf
	v_mov_b32_e32 v254, 0
	v_mov_b32_e32 v255, 0
	v_add_u32_dpp v251, v251, v251 quad_perm:[2,3,0,1] row_mask:0xf bank_mask:0xf
	s_nop 1
	v_add_u32_dpp v251, v251, v251 row_half_mirror row_mask:0xf bank_mask:0xf
	s_nop 1
	v_add_u32_dpp v251, v251, v251 row_mirror row_mask:0xf bank_mask:0xf
	s_nop 1
	v_readlane_b32 s30, v251, 0
	v_readlane_b32 s54, v251, 16
	v_readlane_b32 s55, v251, 32
	v_readlane_b32 s56, v251, 48
	s_add_i32 s30, s30, s54
	s_add_i32 s55, s55, s56
	s_add_i32 s30, s30, s55
	s_sub_i32 s30, 0xe00, s30
	s_cmpk_lt_u32 s30, 0x100
	s_cselect_b32 s58, s58, s60
	s_cmpk_eq_i32 s30, 0x100
	s_cbranch_scc1 .Lbq_exit
	s_sub_u32 s59, s59, 1
	s_cbranch_scc1 .Lbq_exit
	s_lshl_b32 s60, 1, s59
	s_or_b32 s60, s60, s58
	s_branch .Lbq7_loop
.Lbq6_loop:
	v_subrev_u32_e32 v252, s60, v41
	v_subrev_u32_e32 v253, s60, v39
	v_alignbit_b32 v254, v254, v252, 31
	v_alignbit_b32 v255, v255, v253, 31
	v_subrev_u32_e32 v252, s60, v38
	v_subrev_u32_e32 v253, s60, v37
	v_alignbit_b32 v254, v254, v252, 31
	v_alignbit_b32 v255, v255, v253, 31
	v_subrev_u32_e32 v252, s60, v1
	v_subrev_u32_e32 v253, s60, v0
	v_alignbit_b32 v254, v254, v252, 31
	v_alignbit_b32 v255, v255, v253, 31
	v_subrev_u32_e32 v252, s60, v3
	v_subrev_u32_e32 v253, s60, v2
	v_alignbit_b32 v254, v254, v252, 31
	v_alignbit_b32 v255, v255, v253, 31
	v_subrev_u32_e32 v252, s60, v5
	v_subrev_u32_e32 v253, s60, v4
	v_alignbit_b32 v254, v254, v252, 31
	v_alignbit_b32 v255, v255, v253, 31
	v_subrev_u32_e32 v252, s60, v7
	v_subrev_u32_e32 v253, s60, v6
	v_alignbit_b32 v254, v254, v252, 31
	v_alignbit_b32 v255, v255, v253, 31
	v_subrev_u32_e32 v252, s60, v9
	v_subrev_u32_e32 v253, s60, v8
	v_alignbit_b32 v254, v254, v252, 31
	v_alignbit_b32 v255, v255, v253, 31
	v_subrev_u32_e32 v252, s60, v11
	v_subrev_u32_e32 v253, s60, v10
	v_alignbit_b32 v254, v254, v252, 31
	v_alignbit_b32 v255, v255, v253, 31
	v_subrev_u32_e32 v252, s60, v13
	v_subrev_u32_e32 v253, s60, v12
	v_alignbit_b32 v254, v254, v252, 31
	v_alignbit_b32 v255, v255, v253, 31
	v_subrev_u32_e32 v252, s60, v15
	v_subrev_u32_e32 v253, s60, v14
	v_alignbit_b32 v254, v254, v252, 31
	v_alignbit_b32 v255, v255, v253, 31
	v_subrev_u32_e32 v252, s60, v17
	v_subrev_u32_e32 v253, s60, v16
	v_alignbit_b32 v254, v254, v252, 31
	v_alignbit_b32 v255, v255, v253, 31
	v_subrev_u32_e32 v252, s60, v19
	v_subrev_u32_e32 v253, s60, v18
	v_alignbit_b32 v254, v254, v252, 31
	v_alignbit_b32 v255, v255, v253, 31
	v_subrev_u32_e32 v252, s60, v21
	v_subrev_u32_e32 v253, s60, v20
	v_alignbit_b32 v254, v254, v252, 31
	v_alignbit_b32 v255, v255, v253, 31
	v_subrev_u32_e32 v252, s60, v23
	v_subrev_u32_e32 v253, s60, v22
	v_alignbit_b32 v254, v254, v252, 31
	v_alignbit_b32 v255, v255, v253, 31
	v_subrev_u32_e32 v252, s60, v25
	v_subrev_u32_e32 v253, s60, v24
	v_alignbit_b32 v254, v254, v252, 31
	v_alignbit_b32 v255, v255, v253, 31
	v_subrev_u32_e32 v252, s60, v27
	v_subrev_u32_e32 v253, s60, v26
	v_alignbit_b32 v254, v254, v252, 31
	v_alignbit_b32 v255, v255, v253, 31
	v_subrev_u32_e32 v252, s60, v29
	v_subrev_u32_e32 v253, s60, v28
	v_alignbit_b32 v254, v254, v252, 31
	v_alignbit_b32 v255, v255, v253, 31
	v_subrev_u32_e32 v252, s60, v31
	v_subrev_u32_e32 v253, s60, v30
	v_alignbit_b32 v254, v254, v252, 31
	v_alignbit_b32 v255, v255, v253, 31
	v_subrev_u32_e32 v252, s60, v33
	v_subrev_u32_e32 v253, s60, v32
	v_alignbit_b32 v254, v254, v252, 31
	v_alignbit_b32 v255, v255, v253, 31
	v_subrev_u32_e32 v252, s60, v35
	v_subrev_u32_e32 v253, s60, v34
	v_alignbit_b32 v254, v254, v252, 31
	v_alignbit_b32 v255, v255, v253, 31
	v_subrev_u32_e32 v252, s60, v40
	v_subrev_u32_e32 v253, s60, v36
	v_alignbit_b32 v254, v254, v252, 31
	v_alignbit_b32 v255, v255, v253, 31
	v_subrev_u32_e32 v252, s60, v43
	v_subrev_u32_e32 v253, s60, v42
	v_alignbit_b32 v254, v254, v252, 31
	v_alignbit_b32 v255, v255, v253, 31
	v_subrev_u32_e32 v252, s60, v46
	v_subrev_u32_e32 v253, s60, v45
	v_alignbit_b32 v254, v254, v252, 31
	v_alignbit_b32 v255, v255, v253, 31
	v_subrev_u32_e32 v252, s60, v48
	v_subrev_u32_e32 v253, s60, v47
	v_alignbit_b32 v254, v254, v252, 31
	v_alignbit_b32 v255, v255, v253, 31
	v_bcnt_u32_b32 v251, v254, 0
	v_bcnt_u32_b32 v251, v255, v251
	s_nop 1
	v_add_u32_dpp v251, v251, v251 quad_perm:[1,0,3,2] row_mask:0xf bank_mask:0xf
	v_mov_b32_e32 v254, 0
	v_mov_b32_e32 v255, 0
	v_add_u32_dpp v251, v251, v251 quad_perm:[2,3,0,1] row_mask:0xf bank_mask:0xf
	s_nop 1
	v_add_u32_dpp v251, v251, v251 row_half_mirror row_mask:0xf bank_mask:0xf
	s_nop 1
	v_add_u32_dpp v251, v251, v251 row_mirror row_mask:0xf bank_mask:0xf
	s_nop 1
	v_readlane_b32 s30, v251, 0
	v_readlane_b32 s54, v251, 16
	v_readlane_b32 s55, v251, 32
	v_readlane_b32 s56, v251, 48
	s_add_i32 s30, s30, s54
	s_add_i32 s55, s55, s56
	s_add_i32 s30, s30, s55
	s_sub_i32 s30, 0xc00, s30
	s_cmpk_lt_u32 s30, 0x100
	s_cselect_b32 s58, s58, s60
	s_cmpk_eq_i32 s30, 0x100
	s_cbranch_scc1 .Lbq_exit
	s_sub_u32 s59, s59, 1
	s_cbranch_scc1 .Lbq_exit
	s_lshl_b32 s60, 1, s59
	s_or_b32 s60, s60, s58
	s_branch .Lbq6_loop
.Lbq5_loop:
	v_subrev_u32_e32 v252, s60, v41
	v_subrev_u32_e32 v253, s60, v39
	v_alignbit_b32 v254, v254, v252, 31
	v_alignbit_b32 v255, v255, v253, 31
	v_subrev_u32_e32 v252, s60, v38
	v_subrev_u32_e32 v253, s60, v37
	v_alignbit_b32 v254, v254, v252, 31
	v_alignbit_b32 v255, v255, v253, 31
	v_subrev_u32_e32 v252, s60, v1
	v_subrev_u32_e32 v253, s60, v0
	v_alignbit_b32 v254, v254, v252, 31
	v_alignbit_b32 v255, v255, v253, 31
	v_subrev_u32_e32 v252, s60, v3
	v_subrev_u32_e32 v253, s60, v2
	v_alignbit_b32 v254, v254, v252, 31
	v_alignbit_b32 v255, v255, v253, 31
	v_subrev_u32_e32 v252, s60, v5
	v_subrev_u32_e32 v253, s60, v4
	v_alignbit_b32 v254, v254, v252, 31
	v_alignbit_b32 v255, v255, v253, 31
	v_subrev_u32_e32 v252, s60, v7
	v_subrev_u32_e32 v253, s60, v6
	v_alignbit_b32 v254, v254, v252, 31
	v_alignbit_b32 v255, v255, v253, 31
	v_subrev_u32_e32 v252, s60, v9
	v_subrev_u32_e32 v253, s60, v8
	v_alignbit_b32 v254, v254, v252, 31
	v_alignbit_b32 v255, v255, v253, 31
	v_subrev_u32_e32 v252, s60, v11
	v_subrev_u32_e32 v253, s60, v10
	v_alignbit_b32 v254, v254, v252, 31
	v_alignbit_b32 v255, v255, v253, 31
	v_subrev_u32_e32 v252, s60, v13
	v_subrev_u32_e32 v253, s60, v12
	v_alignbit_b32 v254, v254, v252, 31
	v_alignbit_b32 v255, v255, v253, 31
	v_subrev_u32_e32 v252, s60, v15
	v_subrev_u32_e32 v253, s60, v14
	v_alignbit_b32 v254, v254, v252, 31
	v_alignbit_b32 v255, v255, v253, 31
	v_subrev_u32_e32 v252, s60, v17
	v_subrev_u32_e32 v253, s60, v16
	v_alignbit_b32 v254, v254, v252, 31
	v_alignbit_b32 v255, v255, v253, 31
	v_subrev_u32_e32 v252, s60, v19
	v_subrev_u32_e32 v253, s60, v18
	v_alignbit_b32 v254, v254, v252, 31
	v_alignbit_b32 v255, v255, v253, 31
	v_subrev_u32_e32 v252, s60, v21
	v_subrev_u32_e32 v253, s60, v20
	v_alignbit_b32 v254, v254, v252, 31
	v_alignbit_b32 v255, v255, v253, 31
	v_subrev_u32_e32 v252, s60, v23
	v_subrev_u32_e32 v253, s60, v22
	v_alignbit_b32 v254, v254, v252, 31
	v_alignbit_b32 v255, v255, v253, 31
	v_subrev_u32_e32 v252, s60, v25
	v_subrev_u32_e32 v253, s60, v24
	v_alignbit_b32 v254, v254, v252, 31
	v_alignbit_b32 v255, v255, v253, 31
	v_subrev_u32_e32 v252, s60, v27
	v_subrev_u32_e32 v253, s60, v26
	v_alignbit_b32 v254, v254, v252, 31
	v_alignbit_b32 v255, v255, v253, 31
	v_subrev_u32_e32 v252, s60, v29
	v_subrev_u32_e32 v253, s60, v28
	v_alignbit_b32 v254, v254, v252, 31
	v_alignbit_b32 v255, v255, v253, 31
	v_subrev_u32_e32 v252, s60, v31
	v_subrev_u32_e32 v253, s60, v30
	v_alignbit_b32 v254, v254, v252, 31
	v_alignbit_b32 v255, v255, v253, 31
	v_subrev_u32_e32 v252, s60, v33
	v_subrev_u32_e32 v253, s60, v32
	v_alignbit_b32 v254, v254, v252, 31
	v_alignbit_b32 v255, v255, v253, 31
	v_subrev_u32_e32 v252, s60, v35
	v_subrev_u32_e32 v253, s60, v34
	v_alignbit_b32 v254, v254, v252, 31
	v_alignbit_b32 v255, v255, v253, 31
	v_bcnt_u32_b32 v251, v254, 0
	v_bcnt_u32_b32 v251, v255, v251
	s_nop 1
	v_add_u32_dpp v251, v251, v251 quad_perm:[1,0,3,2] row_mask:0xf bank_mask:0xf
	v_mov_b32_e32 v254, 0
	v_mov_b32_e32 v255, 0
	v_add_u32_dpp v251, v251, v251 quad_perm:[2,3,0,1] row_mask:0xf bank_mask:0xf
	s_nop 1
	v_add_u32_dpp v251, v251, v251 row_half_mirror row_mask:0xf bank_mask:0xf
	s_nop 1
	v_add_u32_dpp v251, v251, v251 row_mirror row_mask:0xf bank_mask:0xf
	s_nop 1
	v_readlane_b32 s30, v251, 0
	v_readlane_b32 s54, v251, 16
	v_readlane_b32 s55, v251, 32
	v_readlane_b32 s56, v251, 48
	s_add_i32 s30, s30, s54
	s_add_i32 s55, s55, s56
	s_add_i32 s30, s30, s55
	s_sub_i32 s30, 0xa00, s30
	s_cmpk_lt_u32 s30, 0x100
	s_cselect_b32 s58, s58, s60
	s_cmpk_eq_i32 s30, 0x100
	s_cbranch_scc1 .Lbq_exit
	s_sub_u32 s59, s59, 1
	s_cbranch_scc1 .Lbq_exit
	s_lshl_b32 s60, 1, s59
	s_or_b32 s60, s60, s58
	s_branch .Lbq5_loop
.Lbq4_loop:
	v_subrev_u32_e32 v252, s60, v41
	v_subrev_u32_e32 v253, s60, v39
	v_alignbit_b32 v254, v254, v252, 31
	v_alignbit_b32 v255, v255, v253, 31
	v_subrev_u32_e32 v252, s60, v38
	v_subrev_u32_e32 v253, s60, v37
	v_alignbit_b32 v254, v254, v252, 31
	v_alignbit_b32 v255, v255, v253, 31
	v_subrev_u32_e32 v252, s60, v1
	v_subrev_u32_e32 v253, s60, v0
	v_alignbit_b32 v254, v254, v252, 31
	v_alignbit_b32 v255, v255, v253, 31
	v_subrev_u32_e32 v252, s60, v3
	v_subrev_u32_e32 v253, s60, v2
	v_alignbit_b32 v254, v254, v252, 31
	v_alignbit_b32 v255, v255, v253, 31
	v_subrev_u32_e32 v252, s60, v5
	v_subrev_u32_e32 v253, s60, v4
	v_alignbit_b32 v254, v254, v252, 31
	v_alignbit_b32 v255, v255, v253, 31
	v_subrev_u32_e32 v252, s60, v7
	v_subrev_u32_e32 v253, s60, v6
	v_alignbit_b32 v254, v254, v252, 31
	v_alignbit_b32 v255, v255, v253, 31
	v_subrev_u32_e32 v252, s60, v9
	v_subrev_u32_e32 v253, s60, v8
	v_alignbit_b32 v254, v254, v252, 31
	v_alignbit_b32 v255, v255, v253, 31
	v_subrev_u32_e32 v252, s60, v11
	v_subrev_u32_e32 v253, s60, v10
	v_alignbit_b32 v254, v254, v252, 31
	v_alignbit_b32 v255, v255, v253, 31
	v_subrev_u32_e32 v252, s60, v13
	v_subrev_u32_e32 v253, s60, v12
	v_alignbit_b32 v254, v254, v252, 31
	v_alignbit_b32 v255, v255, v253, 31
	v_subrev_u32_e32 v252, s60, v15
	v_subrev_u32_e32 v253, s60, v14
	v_alignbit_b32 v254, v254, v252, 31
	v_alignbit_b32 v255, v255, v253, 31
	v_subrev_u32_e32 v252, s60, v17
	v_subrev_u32_e32 v253, s60, v16
	v_alignbit_b32 v254, v254, v252, 31
	v_alignbit_b32 v255, v255, v253, 31
	v_subrev_u32_e32 v252, s60, v19
	v_subrev_u32_e32 v253, s60, v18
	v_alignbit_b32 v254, v254, v252, 31
	v_alignbit_b32 v255, v255, v253, 31
	v_subrev_u32_e32 v252, s60, v21
	v_subrev_u32_e32 v253, s60, v20
	v_alignbit_b32 v254, v254, v252, 31
	v_alignbit_b32 v255, v255, v253, 31
	v_subrev_u32_e32 v252, s60, v23
	v_subrev_u32_e32 v253, s60, v22
	v_alignbit_b32 v254, v254, v252, 31
	v_alignbit_b32 v255, v255, v253, 31
	v_subrev_u32_e32 v252, s60, v25
	v_subrev_u32_e32 v253, s60, v24
	v_alignbit_b32 v254, v254, v252, 31
	v_alignbit_b32 v255, v255, v253, 31
	v_subrev_u32_e32 v252, s60, v27
	v_subrev_u32_e32 v253, s60, v26
	v_alignbit_b32 v254, v254, v252, 31
	v_alignbit_b32 v255, v255, v253, 31
	v_bcnt_u32_b32 v251, v254, 0
	v_bcnt_u32_b32 v251, v255, v251
	s_nop 1
	v_add_u32_dpp v251, v251, v251 quad_perm:[1,0,3,2] row_mask:0xf bank_mask:0xf
	v_mov_b32_e32 v254, 0
	v_mov_b32_e32 v255, 0
	v_add_u32_dpp v251, v251, v251 quad_perm:[2,3,0,1] row_mask:0xf bank_mask:0xf
	s_nop 1
	v_add_u32_dpp v251, v251, v251 row_half_mirror row_mask:0xf bank_mask:0xf
	s_nop 1
	v_add_u32_dpp v251, v251, v251 row_mirror row_mask:0xf bank_mask:0xf
	s_nop 1
	v_readlane_b32 s30, v251, 0
	v_readlane_b32 s54, v251, 16
	v_readlane_b32 s55, v251, 32
	v_readlane_b32 s56, v251, 48
	s_add_i32 s30, s30, s54
	s_add_i32 s55, s55, s56
	s_add_i32 s30, s30, s55
	s_sub_i32 s30, 0x800, s30
	s_cmpk_lt_u32 s30, 0x100
	s_cselect_b32 s58, s58, s60
	s_cmpk_eq_i32 s30, 0x100
	s_cbranch_scc1 .Lbq_exit
	s_sub_u32 s59, s59, 1
	s_cbranch_scc1 .Lbq_exit
	s_lshl_b32 s60, 1, s59
	s_or_b32 s60, s60, s58
	s_branch .Lbq4_loop
.Lbq3_loop:
	v_subrev_u32_e32 v252, s60, v41
	v_subrev_u32_e32 v253, s60, v39
	v_alignbit_b32 v254, v254, v252, 31
	v_alignbit_b32 v255, v255, v253, 31
	v_subrev_u32_e32 v252, s60, v38
	v_subrev_u32_e32 v253, s60, v37
	v_alignbit_b32 v254, v254, v252, 31
	v_alignbit_b32 v255, v255, v253, 31
	v_subrev_u32_e32 v252, s60, v1
	v_subrev_u32_e32 v253, s60, v0
	v_alignbit_b32 v254, v254, v252, 31
	v_alignbit_b32 v255, v255, v253, 31
	v_subrev_u32_e32 v252, s60, v3
	v_subrev_u32_e32 v253, s60, v2
	v_alignbit_b32 v254, v254, v252, 31
	v_alignbit_b32 v255, v255, v253, 31
	v_subrev_u32_e32 v252, s60, v5
	v_subrev_u32_e32 v253, s60, v4
	v_alignbit_b32 v254, v254, v252, 31
	v_alignbit_b32 v255, v255, v253, 31
	v_subrev_u32_e32 v252, s60, v7
	v_subrev_u32_e32 v253, s60, v6
	v_alignbit_b32 v254, v254, v252, 31
	v_alignbit_b32 v255, v255, v253, 31
	v_subrev_u32_e32 v252, s60, v9
	v_subrev_u32_e32 v253, s60, v8
	v_alignbit_b32 v254, v254, v252, 31
	v_alignbit_b32 v255, v255, v253, 31
	v_subrev_u32_e32 v252, s60, v11
	v_subrev_u32_e32 v253, s60, v10
	v_alignbit_b32 v254, v254, v252, 31
	v_alignbit_b32 v255, v255, v253, 31
	v_subrev_u32_e32 v252, s60, v13
	v_subrev_u32_e32 v253, s60, v12
	v_alignbit_b32 v254, v254, v252, 31
	v_alignbit_b32 v255, v255, v253, 31
	v_subrev_u32_e32 v252, s60, v15
	v_subrev_u32_e32 v253, s60, v14
	v_alignbit_b32 v254, v254, v252, 31
	v_alignbit_b32 v255, v255, v253, 31
	v_subrev_u32_e32 v252, s60, v17
	v_subrev_u32_e32 v253, s60, v16
	v_alignbit_b32 v254, v254, v252, 31
	v_alignbit_b32 v255, v255, v253, 31
	v_subrev_u32_e32 v252, s60, v19
	v_subrev_u32_e32 v253, s60, v18
	v_alignbit_b32 v254, v254, v252, 31
	v_alignbit_b32 v255, v255, v253, 31
	v_bcnt_u32_b32 v251, v254, 0
	v_bcnt_u32_b32 v251, v255, v251
	s_nop 1
	v_add_u32_dpp v251, v251, v251 quad_perm:[1,0,3,2] row_mask:0xf bank_mask:0xf
	v_mov_b32_e32 v254, 0
	v_mov_b32_e32 v255, 0
	v_add_u32_dpp v251, v251, v251 quad_perm:[2,3,0,1] row_mask:0xf bank_mask:0xf
	s_nop 1
	v_add_u32_dpp v251, v251, v251 row_half_mirror row_mask:0xf bank_mask:0xf
	s_nop 1
	v_add_u32_dpp v251, v251, v251 row_mirror row_mask:0xf bank_mask:0xf
	s_nop 1
	v_readlane_b32 s30, v251, 0
	v_readlane_b32 s54, v251, 16
	v_readlane_b32 s55, v251, 32
	v_readlane_b32 s56, v251, 48
	s_add_i32 s30, s30, s54
	s_add_i32 s55, s55, s56
	s_add_i32 s30, s30, s55
	s_sub_i32 s30, 0x600, s30
	s_cmpk_lt_u32 s30, 0x100
	s_cselect_b32 s58, s58, s60
	s_cmpk_eq_i32 s30, 0x100
	s_cbranch_scc1 .Lbq_exit
	s_sub_u32 s59, s59, 1
	s_cbranch_scc1 .Lbq_exit
	s_lshl_b32 s60, 1, s59
	s_or_b32 s60, s60, s58
	s_branch .Lbq3_loop
.Lbq2_loop:
	v_subrev_u32_e32 v252, s60, v41
	v_subrev_u32_e32 v253, s60, v39
	v_alignbit_b32 v254, v254, v252, 31
	v_alignbit_b32 v255, v255, v253, 31
	v_subrev_u32_e32 v252, s60, v38
	v_subrev_u32_e32 v253, s60, v37
	v_alignbit_b32 v254, v254, v252, 31
	v_alignbit_b32 v255, v255, v253, 31
	v_subrev_u32_e32 v252, s60, v1
	v_subrev_u32_e32 v253, s60, v0
	v_alignbit_b32 v254, v254, v252, 31
	v_alignbit_b32 v255, v255, v253, 31
	v_subrev_u32_e32 v252, s60, v3
	v_subrev_u32_e32 v253, s60, v2
	v_alignbit_b32 v254, v254, v252, 31
	v_alignbit_b32 v255, v255, v253, 31
	v_subrev_u32_e32 v252, s60, v5
	v_subrev_u32_e32 v253, s60, v4
	v_alignbit_b32 v254, v254, v252, 31
	v_alignbit_b32 v255, v255, v253, 31
	v_subrev_u32_e32 v252, s60, v7
	v_subrev_u32_e32 v253, s60, v6
	v_alignbit_b32 v254, v254, v252, 31
	v_alignbit_b32 v255, v255, v253, 31
	v_subrev_u32_e32 v252, s60, v9
	v_subrev_u32_e32 v253, s60, v8
	v_alignbit_b32 v254, v254, v252, 31
	v_alignbit_b32 v255, v255, v253, 31
	v_subrev_u32_e32 v252, s60, v11
	v_subrev_u32_e32 v253, s60, v10
	v_alignbit_b32 v254, v254, v252, 31
	v_alignbit_b32 v255, v255, v253, 31
	v_bcnt_u32_b32 v251, v254, 0
	v_bcnt_u32_b32 v251, v255, v251
	s_nop 1
	v_add_u32_dpp v251, v251, v251 quad_perm:[1,0,3,2] row_mask:0xf bank_mask:0xf
	v_mov_b32_e32 v254, 0
	v_mov_b32_e32 v255, 0
	v_add_u32_dpp v251, v251, v251 quad_perm:[2,3,0,1] row_mask:0xf bank_mask:0xf
	s_nop 1
	v_add_u32_dpp v251, v251, v251 row_half_mirror row_mask:0xf bank_mask:0xf
	s_nop 1
	v_add_u32_dpp v251, v251, v251 row_mirror row_mask:0xf bank_mask:0xf
	s_nop 1
	v_readlane_b32 s30, v251, 0
	v_readlane_b32 s54, v251, 16
	v_readlane_b32 s55, v251, 32
	v_readlane_b32 s56, v251, 48
	s_add_i32 s30, s30, s54
	s_add_i32 s55, s55, s56
	s_add_i32 s30, s30, s55
	s_sub_i32 s30, 0x400, s30
	s_cmpk_lt_u32 s30, 0x100
	s_cselect_b32 s58, s58, s60
	s_cmpk_eq_i32 s30, 0x100
	s_cbranch_scc1 .Lbq_exit
	s_sub_u32 s59, s59, 1
	s_cbranch_scc1 .Lbq_exit
	s_lshl_b32 s60, 1, s59
	s_or_b32 s60, s60, s58
	s_branch .Lbq2_loop
.Lbq1_loop:
	v_subrev_u32_e32 v252, s60, v41
	v_subrev_u32_e32 v253, s60, v39
	v_alignbit_b32 v254, v254, v252, 31
	v_alignbit_b32 v255, v255, v253, 31
	v_subrev_u32_e32 v252, s60, v38
	v_subrev_u32_e32 v253, s60, v37
	v_alignbit_b32 v254, v254, v252, 31
	v_alignbit_b32 v255, v255, v253, 31
	v_subrev_u32_e32 v252, s60, v1
	v_subrev_u32_e32 v253, s60, v0
	v_alignbit_b32 v254, v254, v252, 31
	v_alignbit_b32 v255, v255, v253, 31
	v_subrev_u32_e32 v252, s60, v3
	v_subrev_u32_e32 v253, s60, v2
	v_alignbit_b32 v254, v254, v252, 31
	v_alignbit_b32 v255, v255, v253, 31
	v_bcnt_u32_b32 v251, v254, 0
	v_bcnt_u32_b32 v251, v255, v251
	s_nop 1
	v_add_u32_dpp v251, v251, v251 quad_perm:[1,0,3,2] row_mask:0xf bank_mask:0xf
	v_mov_b32_e32 v254, 0
	v_mov_b32_e32 v255, 0
	v_add_u32_dpp v251, v251, v251 quad_perm:[2,3,0,1] row_mask:0xf bank_mask:0xf
	s_nop 1
	v_add_u32_dpp v251, v251, v251 row_half_mirror row_mask:0xf bank_mask:0xf
	s_nop 1
	v_add_u32_dpp v251, v251, v251 row_mirror row_mask:0xf bank_mask:0xf
	s_nop 1
	v_readlane_b32 s30, v251, 0
	v_readlane_b32 s54, v251, 16
	v_readlane_b32 s55, v251, 32
	v_readlane_b32 s56, v251, 48
	s_add_i32 s30, s30, s54
	s_add_i32 s55, s55, s56
	s_add_i32 s30, s30, s55
	s_sub_i32 s30, 0x200, s30
	s_cmpk_lt_u32 s30, 0x100
	s_cselect_b32 s58, s58, s60
	s_cmpk_eq_i32 s30, 0x100
	s_cbranch_scc1 .Lbq_exit
	s_sub_u32 s59, s59, 1
	s_cbranch_scc1 .Lbq_exit
	s_lshl_b32 s60, 1, s59
	s_or_b32 s60, s60, s58
	s_branch .Lbq1_loop
.Lbq_exit:
	v_mov_b32_e32 v44, s58
	s_branch .LBB0_643

.LBB0_868:
	s_and_b32 s44, s2, 1
	s_xor_b32 s49, s44, 1
	s_mulk_i32 s49, 0x2400
	s_mulk_i32 s44, 0x2400
	v_add_u32_e32 v80, s44, v129
	v_add_u32_e32 v113, s49, v127
	v_add_u32_e32 v76, s44, v167
	ds_read_b128 v[202:205], v80 offset:4608
	ds_read_b128 v[206:209], v80 offset:4672
	ds_read_b128 v[210:213], v80 offset:6912
	ds_read_b128 v[218:221], v80 offset:6976
	v_lshrrev_b64 v[246:247], s2, v[72:73]
	v_lshrrev_b64 v[244:245], s2, v[74:75]
	v_add_u32_e32 v80, s49, v129
	v_not_b32_e32 v246, v246
	v_not_b32_e32 v247, v244
	v_bfe_i32 v246, v246, 0, 1
	v_bfe_i32 v247, v247, 0, 1
	v_and_b32_e32 v238, 0xf149f2ca, v246
	v_and_b32_e32 v242, 0xf149f2ca, v247
	v_and_b32_e32 v239, 0xf149f2ca, v246
	v_and_b32_e32 v243, 0xf149f2ca, v247
	v_and_b32_e32 v240, 0xf149f2ca, v246
	v_and_b32_e32 v244, 0xf149f2ca, v247
	v_and_b32_e32 v241, 0xf149f2ca, v246
	v_and_b32_e32 v245, 0xf149f2ca, v247
	s_waitcnt lgkmcnt(5)
	v_mfma_f32_16x16x32_bf16 v[64:67], v[186:189], v[0:3], v[238:241]
	v_mfma_f32_16x16x32_bf16 v[68:71], v[186:189], v[8:11], v[242:245]
	v_mfma_f32_16x16x32_bf16 v[222:225], v[194:197], v[0:3], v[238:241]
	v_mfma_f32_16x16x32_bf16 v[226:229], v[194:197], v[8:11], v[242:245]
	s_waitcnt vmcnt(2)
	ds_write_b128 v113, v[52:55]
	ds_write_b128 v113, v[48:51] offset:18432
	s_waitcnt lgkmcnt(6)
	v_mfma_f32_16x16x32_bf16 v[64:67], v[190:193], v[4:7], v[64:67]
	v_mfma_f32_16x16x32_bf16 v[68:71], v[190:193], v[12:15], v[68:71]
	v_mfma_f32_16x16x32_bf16 v[222:225], v[198:201], v[4:7], v[222:225]
	v_mfma_f32_16x16x32_bf16 v[226:229], v[198:201], v[12:15], v[226:229]
	s_waitcnt vmcnt(0)
	ds_write_b128 v113, v[56:59] offset:4608
	ds_write_b128 v113, v[60:63] offset:23040
	s_add_i32 s48, s2, 2
	s_min_i32 s48, s48, s47
	s_lshl_b32 s44, s48, 6
	s_lshl_b64 s[48:49], s[44:45], 7
	v_lshl_add_u64 v[52:53], v[158:159], 0, s[48:49]
	v_lshl_add_u64 v[48:49], s[44:45], 1, v[156:157]
	s_or_b32 s44, s44, 32
	s_lshl_b64 s[48:49], s[44:45], 7
	global_load_dwordx4 v[52:55], v[52:53], off
	v_lshl_add_u64 v[56:57], v[158:159], 0, s[48:49]
	v_add_co_u32_e32 v60, vcc, s50, v48
	s_nop 0
	v_addc_co_u32_e32 v61, vcc, 0, v49, vcc
	global_load_dwordx4 v[48:51], v[48:49], off
	global_load_dwordx4 v[56:59], v[56:57], off
	global_load_dwordx4 v[60:63], v[60:61], off
	ds_read_b64 v[186:187], v76 offset:18432
	ds_read_b64 v[188:189], v76 offset:18464
	ds_read_b64 v[190:191], v76 offset:20736
	ds_read_b64 v[192:193], v76 offset:20768
	ds_read_b64 v[194:195], v76 offset:23040
	ds_read_b64 v[196:197], v76 offset:23072
	ds_read_b64 v[198:199], v76 offset:25344
	s_waitcnt lgkmcnt(13)
	ds_read_b64 v[200:201], v76 offset:25376
	s_waitcnt lgkmcnt(13)
	v_mfma_f32_16x16x32_bf16 v[230:233], v[202:205], v[0:3], v[238:241]
	v_mfma_f32_16x16x32_bf16 v[234:237], v[202:205], v[8:11], v[242:245]
	v_mfma_f32_16x16x32_bf16 v[238:241], v[210:213], v[0:3], v[238:241]
	v_mfma_f32_16x16x32_bf16 v[242:245], v[210:213], v[8:11], v[242:245]
	s_waitcnt lgkmcnt(12)
	v_mfma_f32_16x16x32_bf16 v[230:233], v[206:209], v[4:7], v[230:233]
	v_mfma_f32_16x16x32_bf16 v[234:237], v[206:209], v[12:15], v[234:237]
	v_mfma_f32_16x16x32_bf16 v[238:241], v[218:221], v[4:7], v[238:241]
	v_mfma_f32_16x16x32_bf16 v[242:245], v[218:221], v[12:15], v[242:245]
	ds_read_b64 v[202:203], v76 offset:18496
	ds_read_b64 v[204:205], v76 offset:18528
	ds_read_b64 v[206:207], v76 offset:20800
	s_waitcnt lgkmcnt(13)
	ds_read_b64 v[208:209], v76 offset:20832
	ds_read_b64 v[210:211], v76 offset:23104
	s_waitcnt lgkmcnt(13)
	ds_read_b64 v[212:213], v76 offset:23136
	ds_read_b64 v[218:219], v76 offset:25408
	s_waitcnt lgkmcnt(13)
	ds_read_b64 v[220:221], v76 offset:25440
	s_setprio 0
	s_add_u32 s2, s2, 1
	s_addc_u32 s3, s3, 0
	v_exp_f32_e32 v64, v64
	v_exp_f32_e32 v68, v68
	v_exp_f32_e32 v65, v65
	v_exp_f32_e32 v69, v69
	v_exp_f32_e32 v66, v66
	v_exp_f32_e32 v70, v70
	v_exp_f32_e32 v67, v67
	v_exp_f32_e32 v71, v71
	v_pk_add_f32 v[160:161], v[160:161], v[64:65]
	v_pk_add_f32 v[162:163], v[162:163], v[68:69]
	v_pk_add_f32 v[160:161], v[160:161], v[66:67]
	v_pk_add_f32 v[162:163], v[162:163], v[70:71]
	v_exp_f32_e32 v222, v222
	v_exp_f32_e32 v226, v226
	v_exp_f32_e32 v223, v223
	v_exp_f32_e32 v227, v227
	v_exp_f32_e32 v224, v224
	v_exp_f32_e32 v228, v228
	v_exp_f32_e32 v225, v225
	v_exp_f32_e32 v229, v229
	v_pk_add_f32 v[160:161], v[160:161], v[222:223]
	v_pk_add_f32 v[162:163], v[162:163], v[226:227]
	v_pk_add_f32 v[160:161], v[160:161], v[224:225]
	v_pk_add_f32 v[162:163], v[162:163], v[228:229]
	s_waitcnt lgkmcnt(0)
	s_barrier
	v_cvt_pk_bf16_f32 v64, v64, v65
	v_cvt_pk_bf16_f32 v68, v68, v69
	v_cvt_pk_bf16_f32 v65, v66, v67
	v_cvt_pk_bf16_f32 v69, v70, v71
	v_cvt_pk_bf16_f32 v66, v222, v223
	v_cvt_pk_bf16_f32 v70, v226, v227
	v_cvt_pk_bf16_f32 v67, v224, v225
	v_cvt_pk_bf16_f32 v71, v228, v229
	v_exp_f32_e32 v230, v230
	v_exp_f32_e32 v234, v234
	v_mfma_f32_16x16x32_bf16 v[28:31], v[186:189], v[64:67], v[28:31]
	v_exp_f32_e32 v231, v231
	v_exp_f32_e32 v235, v235
	v_exp_f32_e32 v232, v232
	v_exp_f32_e32 v236, v236
	v_mfma_f32_16x16x32_bf16 v[20:23], v[186:189], v[68:71], v[20:23]
	v_exp_f32_e32 v233, v233
	v_exp_f32_e32 v237, v237
	v_pk_add_f32 v[160:161], v[160:161], v[230:231]
	v_pk_add_f32 v[162:163], v[162:163], v[234:235]
	v_mfma_f32_16x16x32_bf16 v[16:19], v[190:193], v[64:67], v[16:19]
	v_pk_add_f32 v[160:161], v[160:161], v[232:233]
	v_pk_add_f32 v[162:163], v[162:163], v[236:237]
	v_exp_f32_e32 v238, v238
	v_exp_f32_e32 v242, v242
	v_mfma_f32_16x16x32_bf16 v[24:27], v[190:193], v[68:71], v[24:27]
	v_exp_f32_e32 v239, v239
	v_exp_f32_e32 v243, v243
	v_exp_f32_e32 v240, v240
	v_exp_f32_e32 v244, v244
	v_mfma_f32_16x16x32_bf16 v[40:43], v[194:197], v[64:67], v[40:43]
	v_exp_f32_e32 v241, v241
	v_exp_f32_e32 v245, v245
	v_pk_add_f32 v[160:161], v[160:161], v[238:239]
	v_pk_add_f32 v[162:163], v[162:163], v[242:243]
	v_mfma_f32_16x16x32_bf16 v[44:47], v[194:197], v[68:71], v[44:47]
	v_pk_add_f32 v[160:161], v[160:161], v[240:241]
	v_pk_add_f32 v[162:163], v[162:163], v[244:245]
	v_cvt_pk_bf16_f32 v230, v230, v231
	v_cvt_pk_bf16_f32 v234, v234, v235
	v_mfma_f32_16x16x32_bf16 v[36:39], v[198:201], v[64:67], v[36:39]
	v_cvt_pk_bf16_f32 v231, v232, v233
	v_cvt_pk_bf16_f32 v235, v236, v237
	v_cvt_pk_bf16_f32 v232, v238, v239
	v_cvt_pk_bf16_f32 v236, v242, v243
	v_mfma_f32_16x16x32_bf16 v[32:35], v[198:201], v[68:71], v[32:35]
	v_cvt_pk_bf16_f32 v233, v240, v241
	v_cvt_pk_bf16_f32 v237, v244, v245
	ds_read_b128 v[186:189], v80 offset:0
	ds_read_b128 v[190:193], v80 offset:64
	ds_read_b128 v[194:197], v80 offset:2304
	ds_read_b128 v[198:201], v80 offset:2368
	s_setprio 2
	v_mfma_f32_16x16x32_bf16 v[28:31], v[202:205], v[230:233], v[28:31]
	v_mfma_f32_16x16x32_bf16 v[20:23], v[202:205], v[234:237], v[20:23]
	v_mfma_f32_16x16x32_bf16 v[16:19], v[206:209], v[230:233], v[16:19]
	v_mfma_f32_16x16x32_bf16 v[24:27], v[206:209], v[234:237], v[24:27]
	v_mfma_f32_16x16x32_bf16 v[40:43], v[210:213], v[230:233], v[40:43]
	v_mfma_f32_16x16x32_bf16 v[44:47], v[210:213], v[234:237], v[44:47]
	v_mfma_f32_16x16x32_bf16 v[36:39], v[218:221], v[230:233], v[36:39]
	v_mfma_f32_16x16x32_bf16 v[32:35], v[218:221], v[234:237], v[32:35]
	s_cmp_lg_u32 s46, s2
	s_cbranch_scc1 .LBB0_868
	s_waitcnt lgkmcnt(0)
	s_setprio 0
	v_add_f32_e32 v160, v160, v161
	v_add_f32_e32 v161, v162, v163
	s_waitcnt vmcnt(3)
	v_mov_b32_e32 v53, v160
	v_mov_b32_e32 v52, v161

.LBB0_885:
	s_and_b32 s41, s39, 1
	s_xor_b32 s42, s41, 1
	s_mul_i32 s43, s42, 0x2400
	v_add_u32_e32 v199, s43, v127
	s_waitcnt vmcnt(4)
	ds_write_b128 v199, v[16:19]
	s_waitcnt vmcnt(3)
	ds_write_b128 v199, v[20:23] offset:18432
	s_waitcnt vmcnt(1)
	ds_write_b128 v199, v[24:27] offset:4608
	s_waitcnt vmcnt(0)
	ds_write_b128 v199, v[28:31] offset:23040
	v_lshl_or_b32 v217, s42, 8, v169
	ds_write_b64 v217, v[152:153] offset:53376
	v_lshl_add_u32 v217, s41, 8, v78
	s_mulk_i32 s41, 0x2400
	v_add_u32_e32 v251, s41, v129
	v_add_u32_e32 v199, s41, v131
	ds_read_b64 v[212:213], v217 offset:53376
	ds_read_b64 v[246:247], v217 offset:53408
	ds_read_b128 v[218:221], v251 offset:0
	ds_read_b128 v[222:225], v251 offset:64
	ds_read_b128 v[226:229], v251 offset:2304
	ds_read_b128 v[230:233], v251 offset:2368
	ds_read_b128 v[234:237], v251 offset:4608
	ds_read_b128 v[238:241], v251 offset:4672
	ds_read_b128 v[242:245], v251 offset:6912
	ds_read_b128 v[200:203], v251 offset:6976
	s_add_i32 s42, s39, 2
	s_min_i32 s42, s42, s38
	s_lshl_b32 s44, s42, 13
	s_lshl_b32 s46, s42, 7
	s_mov_b32 s47, s45
	s_mov_b32 s43, s45
	v_lshl_add_u64 v[16:17], v[148:149], 0, s[44:45]
	v_lshl_add_u64 v[28:29], v[150:151], 0, s[46:47]
	v_lshl_add_u64 v[152:153], s[42:43], 3, v[146:147]
	global_load_dwordx4 v[16:19], v[16:17], off
	global_load_dwordx4 v[20:23], v[28:29], off
	global_load_dwordx2 v[152:153], v[152:153], off
	s_addk_i32 s44, 0x1000
	s_add_i32 s46, s46, 0x40000
	v_lshl_add_u64 v[24:25], v[148:149], 0, s[44:45]
	v_lshl_add_u64 v[28:29], v[150:151], 0, s[46:47]
	global_load_dwordx4 v[24:27], v[24:25], off
	global_load_dwordx4 v[28:31], v[28:29], off
	s_waitcnt lgkmcnt(8)
	v_lshrrev_b32_e32 v212, v112, v212
	v_lshrrev_b32_e32 v213, v112, v213
	v_lshrrev_b32_e32 v246, v112, v246
	v_lshrrev_b32_e32 v247, v112, v247
	s_waitcnt lgkmcnt(7)
	v_mfma_f32_16x16x32_bf16 v[64:67], v[218:221], v[0:3], 0
	v_mfma_f32_16x16x32_bf16 v[68:71], v[218:221], v[8:11], 0
	ds_read_b64 v[194:195], v199 offset:18432
	ds_read_b64 v[196:197], v199 offset:18464
	s_waitcnt lgkmcnt(8)
	v_mfma_f32_16x16x32_bf16 v[64:67], v[222:225], v[4:7], v[64:67]
	v_mfma_f32_16x16x32_bf16 v[68:71], v[222:225], v[12:15], v[68:71]
	s_waitcnt lgkmcnt(7)
	v_mfma_f32_16x16x32_bf16 v[72:75], v[226:229], v[0:3], 0
	v_mfma_f32_16x16x32_bf16 v[156:159], v[226:229], v[8:11], 0
	ds_read_b64 v[204:205], v199 offset:20736
	ds_read_b64 v[206:207], v199 offset:20768
	s_waitcnt lgkmcnt(8)
	v_mfma_f32_16x16x32_bf16 v[72:75], v[230:233], v[4:7], v[72:75]
	v_mfma_f32_16x16x32_bf16 v[156:159], v[230:233], v[12:15], v[156:159]
	s_waitcnt lgkmcnt(7)
	v_mfma_f32_16x16x32_bf16 v[160:163], v[234:237], v[0:3], 0
	v_mfma_f32_16x16x32_bf16 v[182:185], v[234:237], v[8:11], 0
	ds_read_b64 v[208:209], v199 offset:23040
	ds_read_b64 v[210:211], v199 offset:23072
	s_waitcnt lgkmcnt(8)
	v_mfma_f32_16x16x32_bf16 v[160:163], v[238:241], v[4:7], v[160:163]
	v_mfma_f32_16x16x32_bf16 v[182:185], v[238:241], v[12:15], v[182:185]
	ds_read_b64 v[218:219], v199 offset:18496
	ds_read_b64 v[220:221], v199 offset:18528
	ds_read_b64 v[222:223], v199 offset:20800
	ds_read_b64 v[224:225], v199 offset:20832
	s_waitcnt lgkmcnt(11)
	v_mfma_f32_16x16x32_bf16 v[186:189], v[242:245], v[0:3], 0
	v_mfma_f32_16x16x32_bf16 v[190:193], v[242:245], v[8:11], 0
	ds_read_b64 v[84:85], v199 offset:25344
	ds_read_b64 v[86:87], v199 offset:25376
	s_waitcnt lgkmcnt(12)
	v_mfma_f32_16x16x32_bf16 v[186:189], v[200:203], v[4:7], v[186:189]
	v_mfma_f32_16x16x32_bf16 v[190:193], v[200:203], v[12:15], v[190:193]
	ds_read_b64 v[226:227], v199 offset:23104
	ds_read_b64 v[228:229], v199 offset:23136
	ds_read_b64 v[230:231], v199 offset:25408
	s_waitcnt lgkmcnt(13)
	ds_read_b64 v[232:233], v199 offset:25440
	s_setprio 0
	s_waitcnt lgkmcnt(0)
	s_barrier
	v_exp_f32_e32 v64, v64
	v_exp_f32_e32 v68, v68
	v_exp_f32_e32 v65, v65
	v_exp_f32_e32 v69, v69
	v_bfe_i32 v82, v212, 0, 1
	v_bfe_i32 v145, v246, 0, 1
	v_exp_f32_e32 v66, v66
	v_exp_f32_e32 v70, v70
	v_and_b32_e32 v64, v82, v64
	v_and_b32_e32 v68, v145, v68
	v_bfe_i32 v113, v212, 1, 1
	v_bfe_i32 v198, v246, 1, 1
	v_exp_f32_e32 v67, v67
	v_exp_f32_e32 v71, v71
	v_and_b32_e32 v65, v113, v65
	v_and_b32_e32 v69, v198, v69
	v_add_f32_e32 v155, v155, v64
	v_add_f32_e32 v154, v154, v68
	v_bfe_i32 v82, v212, 2, 1
	v_bfe_i32 v145, v246, 2, 1
	v_and_b32_e32 v66, v82, v66
	v_and_b32_e32 v70, v145, v70
	v_add_f32_e32 v155, v155, v65
	v_add_f32_e32 v154, v154, v69
	v_bfe_i32 v113, v212, 3, 1
	v_bfe_i32 v198, v246, 3, 1
	v_and_b32_e32 v67, v113, v67
	v_and_b32_e32 v71, v198, v71
	v_add_f32_e32 v155, v155, v66
	v_add_f32_e32 v154, v154, v70
	v_add_f32_e32 v155, v155, v67
	v_add_f32_e32 v154, v154, v71
	v_exp_f32_e32 v72, v72
	v_exp_f32_e32 v156, v156
	v_exp_f32_e32 v73, v73
	v_exp_f32_e32 v157, v157
	v_bfe_i32 v82, v212, 16, 1
	v_bfe_i32 v145, v246, 16, 1
	v_exp_f32_e32 v74, v74
	v_exp_f32_e32 v158, v158
	v_and_b32_e32 v72, v82, v72
	v_and_b32_e32 v156, v145, v156
	v_bfe_i32 v113, v212, 17, 1
	v_bfe_i32 v198, v246, 17, 1
	v_exp_f32_e32 v75, v75
	v_exp_f32_e32 v159, v159
	v_and_b32_e32 v73, v113, v73
	v_and_b32_e32 v157, v198, v157
	v_add_f32_e32 v155, v155, v72
	v_add_f32_e32 v154, v154, v156
	v_bfe_i32 v82, v212, 18, 1
	v_bfe_i32 v145, v246, 18, 1
	v_and_b32_e32 v74, v82, v74
	v_and_b32_e32 v158, v145, v158
	v_add_f32_e32 v155, v155, v73
	v_add_f32_e32 v154, v154, v157
	v_bfe_i32 v113, v212, 19, 1
	v_bfe_i32 v198, v246, 19, 1
	v_and_b32_e32 v75, v113, v75
	v_and_b32_e32 v159, v198, v159
	v_add_f32_e32 v155, v155, v74
	v_add_f32_e32 v154, v154, v158
	v_add_f32_e32 v155, v155, v75
	v_add_f32_e32 v154, v154, v159
	v_cvt_pk_bf16_f32 v64, v64, v65
	v_cvt_pk_bf16_f32 v68, v68, v69
	v_cvt_pk_bf16_f32 v65, v66, v67
	v_cvt_pk_bf16_f32 v69, v70, v71
	v_cvt_pk_bf16_f32 v66, v72, v73
	v_cvt_pk_bf16_f32 v70, v156, v157
	v_cvt_pk_bf16_f32 v67, v74, v75
	v_cvt_pk_bf16_f32 v71, v158, v159
	v_exp_f32_e32 v160, v160
	v_exp_f32_e32 v182, v182
	v_mfma_f32_16x16x32_bf16 v[36:39], v[194:197], v[64:67], v[36:39]
	v_exp_f32_e32 v161, v161
	v_exp_f32_e32 v183, v183
	v_bfe_i32 v82, v213, 0, 1
	v_bfe_i32 v145, v247, 0, 1
	v_exp_f32_e32 v162, v162
	v_exp_f32_e32 v184, v184
	v_and_b32_e32 v160, v82, v160
	v_and_b32_e32 v182, v145, v182
	v_bfe_i32 v113, v213, 1, 1
	v_mfma_f32_16x16x32_bf16 v[32:35], v[194:197], v[68:71], v[32:35]
	v_bfe_i32 v198, v247, 1, 1
	v_exp_f32_e32 v163, v163
	v_exp_f32_e32 v185, v185
	v_and_b32_e32 v161, v113, v161
	v_and_b32_e32 v183, v198, v183
	v_add_f32_e32 v155, v155, v160
	v_add_f32_e32 v154, v154, v182
	v_bfe_i32 v82, v213, 2, 1
	v_bfe_i32 v145, v247, 2, 1
	v_mfma_f32_16x16x32_bf16 v[60:63], v[204:207], v[64:67], v[60:63]
	v_and_b32_e32 v162, v82, v162
	v_and_b32_e32 v184, v145, v184
	v_add_f32_e32 v155, v155, v161
	v_add_f32_e32 v154, v154, v183
	v_bfe_i32 v113, v213, 3, 1
	v_bfe_i32 v198, v247, 3, 1
	v_and_b32_e32 v163, v113, v163
	v_and_b32_e32 v185, v198, v185
	v_add_f32_e32 v155, v155, v162
	v_mfma_f32_16x16x32_bf16 v[52:55], v[204:207], v[68:71], v[52:55]
	v_add_f32_e32 v154, v154, v184
	v_add_f32_e32 v155, v155, v163
	v_add_f32_e32 v154, v154, v185
	v_exp_f32_e32 v186, v186
	v_exp_f32_e32 v190, v190
	v_exp_f32_e32 v187, v187
	v_exp_f32_e32 v191, v191
	v_bfe_i32 v82, v213, 16, 1
	v_bfe_i32 v145, v247, 16, 1
	v_mfma_f32_16x16x32_bf16 v[56:59], v[208:211], v[64:67], v[56:59]
	v_exp_f32_e32 v188, v188
	v_exp_f32_e32 v192, v192
	v_and_b32_e32 v186, v82, v186
	v_and_b32_e32 v190, v145, v190
	v_bfe_i32 v113, v213, 17, 1
	v_bfe_i32 v198, v247, 17, 1
	v_exp_f32_e32 v189, v189
	v_exp_f32_e32 v193, v193
	v_and_b32_e32 v187, v113, v187
	v_mfma_f32_16x16x32_bf16 v[44:47], v[208:211], v[68:71], v[44:47]
	v_and_b32_e32 v191, v198, v191
	v_add_f32_e32 v155, v155, v186
	v_add_f32_e32 v154, v154, v190
	v_bfe_i32 v82, v213, 18, 1
	v_bfe_i32 v145, v247, 18, 1
	v_and_b32_e32 v188, v82, v188
	v_and_b32_e32 v192, v145, v192
	v_add_f32_e32 v155, v155, v187
	v_add_f32_e32 v154, v154, v191
	v_mfma_f32_16x16x32_bf16 v[48:51], v[84:87], v[64:67], v[48:51]
	v_bfe_i32 v113, v213, 19, 1
	v_bfe_i32 v198, v247, 19, 1
	v_and_b32_e32 v189, v113, v189
	v_and_b32_e32 v193, v198, v193
	v_add_f32_e32 v155, v155, v188
	v_add_f32_e32 v154, v154, v192
	v_add_f32_e32 v155, v155, v189
	v_add_f32_e32 v154, v154, v193
	v_cvt_pk_bf16_f32 v160, v160, v161
	v_mfma_f32_16x16x32_bf16 v[40:43], v[84:87], v[68:71], v[40:43]
	v_cvt_pk_bf16_f32 v182, v182, v183
	v_cvt_pk_bf16_f32 v161, v162, v163
	v_cvt_pk_bf16_f32 v183, v184, v185
	v_cvt_pk_bf16_f32 v162, v186, v187
	v_cvt_pk_bf16_f32 v184, v190, v191
	v_cvt_pk_bf16_f32 v163, v188, v189
	v_cvt_pk_bf16_f32 v185, v192, v193
	s_add_i32 s39, s39, 1
	s_nop 0
	s_setprio 2
	v_mfma_f32_16x16x32_bf16 v[36:39], v[218:221], v[160:163], v[36:39]
	v_mfma_f32_16x16x32_bf16 v[32:35], v[218:221], v[182:185], v[32:35]
	v_mfma_f32_16x16x32_bf16 v[60:63], v[222:225], v[160:163], v[60:63]
	v_mfma_f32_16x16x32_bf16 v[52:55], v[222:225], v[182:185], v[52:55]
	v_mfma_f32_16x16x32_bf16 v[56:59], v[226:229], v[160:163], v[56:59]
	v_mfma_f32_16x16x32_bf16 v[44:47], v[226:229], v[182:185], v[44:47]
	v_mfma_f32_16x16x32_bf16 v[48:51], v[230:233], v[160:163], v[48:51]
	v_mfma_f32_16x16x32_bf16 v[40:43], v[230:233], v[182:185], v[40:43]
	s_cmp_lg_u32 s40, s39
	s_cbranch_scc1 .LBB0_885
	s_setprio 0
	v_lshlrev_b32_e32 v199, 4, v104
	ds_read_b128 v[84:87], v199 offset:54016
	s_waitcnt lgkmcnt(0)
	v_add_u32_e32 v0, s33, v171
	v_or_b32_e32 v0, s2, v0
	v_mov_b32_e32 v1, s3
	v_lshl_add_u64 v[2:3], v[0:1], 0, v[80:81]
	v_lshlrev_b64 v[2:3], 7, v[2:3]
	v_lshl_add_u64 v[2:3], v[142:143], 0, v[2:3]
	global_load_dwordx2 v[4:5], v[2:3], off
	global_load_dwordx2 v[6:7], v[2:3], off offset:32
	global_load_dwordx2 v[8:9], v[2:3], off offset:64
	v_and_b32_e32 v15, 64, v121
	global_load_dwordx2 v[2:3], v[2:3], off offset:96
	v_xor_b32_e32 v14, 16, v121
	v_add_u32_e32 v15, 64, v15
	v_cmp_lt_i32_e32 vcc, v14, v15
	s_waitcnt vmcnt(8)
	v_xor_b32_e32 v16, 32, v121
	v_lshl_add_u64 v[0:1], v[0:1], 0, v[76:77]
	v_cndmask_b32_e32 v14, v121, v14, vcc
	s_waitcnt vmcnt(7)
	v_lshlrev_b32_e32 v20, 2, v14
	ds_bpermute_b32 v14, v20, v155
	v_cmp_lt_i32_e32 vcc, v16, v15
	v_lshlrev_b64 v[0:1], 7, v[0:1]
	v_lshl_add_u64 v[0:1], v[142:143], 0, v[0:1]
	v_cndmask_b32_e32 v15, v121, v16, vcc
	v_lshlrev_b32_e32 v21, 2, v15
	s_waitcnt lgkmcnt(0)
	v_add_f32_e32 v14, v155, v14
	ds_bpermute_b32 v15, v21, v14
	v_readlane_b32 s48, v250, 24
	v_add_u32_e32 v10, s2, v80
	v_mov_b32_e32 v11, v117
	v_readlane_b32 s49, v250, 25
	s_waitcnt lgkmcnt(0)
	v_add_f32_e32 v22, v14, v15
	global_load_dwordx2 v[14:15], v[0:1], off
	global_load_dwordx2 v[16:17], v[0:1], off offset:32
	global_load_dwordx2 v[18:19], v[0:1], off offset:64
	s_nop 0
	global_load_dwordx2 v[0:1], v[0:1], off offset:96
	v_div_scale_f32 v23, s[38:39], v22, v22, 1.0
	s_waitcnt vmcnt(9)
	v_rcp_f32_e32 v24, v23
	v_div_scale_f32 v25, vcc, 1.0, v22, 1.0
	v_readlane_b32 s60, v250, 36
	v_fma_f32 v26, -v23, v24, 1.0
	v_fmac_f32_e32 v24, v26, v24
	v_mul_f32_e32 v26, v25, v24
	v_fma_f32 v27, -v23, v26, v25
	v_fmac_f32_e32 v26, v27, v24
	v_fma_f32 v23, -v23, v26, v25
	v_div_fmas_f32 v23, v23, v24, v26
	v_readlane_b32 s61, v250, 37
	v_div_fixup_f32 v23, v23, v22, 1.0
	v_cmp_lt_f32_e32 vcc, 0, v22
	v_readlane_b32 s3, v248, 12
	v_lshlrev_b64 v[10:11], 11, v[10:11]
	s_mov_b64 s[48:49], s[60:61]
	v_cndmask_b32_e32 v22, 0, v23, vcc
	v_lshl_or_b32 v12, s3, 9, v179
	v_mov_b32_e32 v13, v117
	v_lshl_add_u64 v[10:11], s[48:49], 0, v[10:11]
	v_mul_f32_e32 v23, v36, v22
	v_mul_f32_e32 v24, v37, v22
	v_mul_f32_e32 v26, v39, v22
	v_mov_b32_e32 v145, v117
	v_lshl_add_u64 v[10:11], v[10:11], 0, v[12:13]
	v_mul_f32_e32 v25, v38, v22
	s_waitcnt vmcnt(8)
	v_mul_f32_e32 v28, v61, v22
	v_mul_f32_e32 v30, v63, v22
	v_lshl_add_u64 v[10:11], v[10:11], 0, v[144:145]
	v_mul_f32_e32 v27, v60, v22
	v_mul_f32_e32 v29, v62, v22
	v_mul_f32_e32 v31, v56, v22
	v_readlane_b32 s50, v250, 26
	v_readlane_b32 s51, v250, 27
	v_readlane_b32 s60, v250, 56
	v_readlane_b32 s61, v250, 57
	v_readlane_b32 s50, v248, 20
	v_readlane_b32 s51, v248, 21
	v_readlane_b32 s52, v250, 28
	v_readlane_b32 s53, v250, 29
	v_readlane_b32 s54, v250, 30
	v_readlane_b32 s55, v250, 31
	v_readlane_b32 s56, v250, 32
	v_readlane_b32 s57, v250, 33
	v_readlane_b32 s58, v250, 34
	v_readlane_b32 s59, v250, 35
	v_readlane_b32 s62, v250, 38
	v_readlane_b32 s63, v250, 39
	s_waitcnt vmcnt(7)
	v_lshlrev_b32_e32 v36, 16, v4
	v_and_b32_e32 v4, 0xffff0000, v4
	v_lshlrev_b32_e32 v37, 16, v5
	v_and_b32_e32 v5, 0xffff0000, v5
	s_waitcnt vmcnt(6)
	v_lshlrev_b32_e32 v38, 16, v6
	v_and_b32_e32 v6, 0xffff0000, v6
	v_lshlrev_b32_e32 v39, 16, v7
	v_and_b32_e32 v7, 0xffff0000, v7
	v_mul_f32_e32 v4, v24, v4
	v_mul_f32_e32 v5, v26, v5
	v_mul_f32_e32 v23, v23, v36
	v_mul_f32_e32 v24, v25, v37
	v_mul_f32_e32 v6, v28, v6
	v_mul_f32_e32 v7, v30, v7
	v_cvt_pk_bf16_f32 v4, v23, v4
	v_cvt_pk_bf16_f32 v5, v24, v5
	v_mul_f32_e32 v25, v27, v38
	v_mul_f32_e32 v26, v29, v39
	v_cvt_pk_bf16_f32 v6, v25, v6
	v_cvt_pk_bf16_f32 v7, v26, v7
	global_store_dwordx2 v[10:11], v[4:5], off offset:1024 sc1
	global_store_dwordx2 v[10:11], v[6:7], off offset:1056 sc1
	v_mul_f32_e32 v4, v57, v22
	s_waitcnt vmcnt(7)
	v_and_b32_e32 v5, 0xffff0000, v8
	v_mul_f32_e32 v4, v4, v5
	v_mul_f32_e32 v5, v58, v22
	v_lshlrev_b32_e32 v6, 16, v9
	v_mul_f32_e32 v5, v5, v6
	v_mul_f32_e32 v6, v59, v22
	v_and_b32_e32 v7, 0xffff0000, v9
	v_mul_f32_e32 v6, v6, v7
	v_cvt_pk_bf16_f32 v5, v5, v6
	ds_bpermute_b32 v6, v20, v154
	v_lshlrev_b32_e32 v56, 16, v8
	v_mul_f32_e32 v27, v31, v56
	v_cvt_pk_bf16_f32 v4, v27, v4
	global_store_dwordx2 v[10:11], v[4:5], off offset:1088 sc1
	v_mul_f32_e32 v4, v48, v22
	s_waitcnt vmcnt(7)
	v_lshlrev_b32_e32 v5, 16, v2
	v_mul_f32_e32 v4, v4, v5
	v_mul_f32_e32 v5, v49, v22
	v_and_b32_e32 v2, 0xffff0000, v2
	v_mul_f32_e32 v2, v5, v2
	s_waitcnt lgkmcnt(0)
	v_add_f32_e32 v5, v154, v6
	ds_bpermute_b32 v6, v21, v5
	v_cvt_pk_bf16_f32 v2, v4, v2
	v_mul_f32_e32 v4, v50, v22
	v_lshlrev_b32_e32 v7, 16, v3
	v_mul_f32_e32 v4, v4, v7
	s_waitcnt lgkmcnt(0)
	v_add_f32_e32 v5, v5, v6
	v_div_scale_f32 v6, s[38:39], v5, v5, 1.0
	v_rcp_f32_e32 v8, v6
	v_mul_f32_e32 v7, v51, v22
	v_and_b32_e32 v3, 0xffff0000, v3
	v_mul_f32_e32 v3, v7, v3
	v_cvt_pk_bf16_f32 v3, v4, v3
	global_store_dwordx2 v[10:11], v[2:3], off offset:1120 sc1
	v_fma_f32 v2, -v6, v8, 1.0
	v_fmac_f32_e32 v8, v2, v8
	v_div_scale_f32 v2, vcc, 1.0, v5, 1.0
	v_mul_f32_e32 v3, v2, v8
	v_fma_f32 v4, -v6, v3, v2
	v_fmac_f32_e32 v3, v4, v8
	v_fma_f32 v2, -v6, v3, v2
	v_div_fmas_f32 v2, v2, v8, v3
	v_div_fixup_f32 v2, v2, v5, 1.0
	v_cmp_lt_f32_e32 vcc, 0, v5
	s_waitcnt vmcnt(7)
	v_lshlrev_b32_e32 v5, 16, v14
	v_mov_b32_e32 v3, v117
	v_cndmask_b32_e32 v6, 0, v2, vcc
	v_mul_f32_e32 v4, v32, v6
	v_add_u32_e32 v2, s2, v76
	v_mul_f32_e32 v4, v4, v5
	v_mul_f32_e32 v5, v33, v6
	v_and_b32_e32 v7, 0xffff0000, v14
	v_lshlrev_b64 v[2:3], 11, v[2:3]
	v_mul_f32_e32 v5, v5, v7
	v_lshl_add_u64 v[2:3], s[48:49], 0, v[2:3]
	v_cvt_pk_bf16_f32 v4, v4, v5
	v_mul_f32_e32 v5, v34, v6
	v_lshlrev_b32_e32 v7, 16, v15
	v_lshl_add_u64 v[2:3], v[2:3], 0, v[12:13]
	v_mul_f32_e32 v5, v5, v7
	v_mul_f32_e32 v7, v35, v6
	v_and_b32_e32 v8, 0xffff0000, v15
	v_lshl_add_u64 v[2:3], v[2:3], 0, v[144:145]
	v_mul_f32_e32 v7, v7, v8
	v_cvt_pk_bf16_f32 v5, v5, v7
	global_store_dwordx2 v[2:3], v[4:5], off offset:1024 sc1
	v_mul_f32_e32 v4, v52, v6
	s_waitcnt vmcnt(7)
	v_lshlrev_b32_e32 v5, 16, v16
	v_mul_f32_e32 v4, v4, v5
	v_mul_f32_e32 v5, v53, v6
	v_and_b32_e32 v7, 0xffff0000, v16
	v_mul_f32_e32 v5, v5, v7
	v_cvt_pk_bf16_f32 v4, v4, v5
	v_mul_f32_e32 v5, v54, v6
	v_lshlrev_b32_e32 v7, 16, v17
	v_mul_f32_e32 v5, v5, v7
	v_mul_f32_e32 v7, v55, v6
	v_and_b32_e32 v8, 0xffff0000, v17
	v_mul_f32_e32 v7, v7, v8
	v_cvt_pk_bf16_f32 v5, v5, v7
	global_store_dwordx2 v[2:3], v[4:5], off offset:1056 sc1
	v_mul_f32_e32 v4, v44, v6
	s_waitcnt vmcnt(7)
	v_lshlrev_b32_e32 v5, 16, v18
	v_mul_f32_e32 v4, v4, v5
	v_mul_f32_e32 v5, v45, v6
	v_and_b32_e32 v7, 0xffff0000, v18
	v_mul_f32_e32 v5, v5, v7
	v_cvt_pk_bf16_f32 v4, v4, v5
	v_mul_f32_e32 v5, v46, v6
	v_lshlrev_b32_e32 v7, 16, v19
	v_mul_f32_e32 v5, v5, v7
	v_mul_f32_e32 v7, v47, v6
	v_and_b32_e32 v8, 0xffff0000, v19
	v_mul_f32_e32 v7, v7, v8
	v_cvt_pk_bf16_f32 v5, v5, v7
	global_store_dwordx2 v[2:3], v[4:5], off offset:1088 sc1
	v_mul_f32_e32 v4, v40, v6
	s_waitcnt vmcnt(7)
	v_lshlrev_b32_e32 v5, 16, v0
	v_mul_f32_e32 v4, v4, v5
	v_mul_f32_e32 v5, v41, v6
	v_and_b32_e32 v0, 0xffff0000, v0
	v_mul_f32_e32 v0, v5, v0
	v_cvt_pk_bf16_f32 v0, v4, v0
	v_mul_f32_e32 v4, v42, v6
	v_lshlrev_b32_e32 v5, 16, v1
	v_mul_f32_e32 v4, v4, v5
	v_mul_f32_e32 v5, v43, v6
	v_and_b32_e32 v1, 0xffff0000, v1
	v_mul_f32_e32 v1, v5, v1
	v_cvt_pk_bf16_f32 v1, v4, v1
	global_store_dwordx2 v[2:3], v[0:1], off offset:1120 sc1
	s_waitcnt vmcnt(0)
	s_mov_b64 s[2:3], s[60:61]
	s_barrier

.LBB0_912:
	s_or_b64 exec, exec, s[8:9]
	s_lshl_b32 s9, s0, 7
	s_lshl_b32 s0, s21, 7
	v_or_b32_e32 v0, s9, v214
	s_and_b32 s8, s0, 0x380
	s_barrier
	v_readfirstlane_b32 s0, v104
	s_and_b32 s10, s0, 64
	s_lshr_b32 s12, s0, 1
	s_and_b32 s12, s12, 0x7fffffc0
	s_lshr_b32 s0, s0, 6
	s_lshl_b32 s0, s0, 10
	v_bfe_u32 v217, v108, 1, 3
	v_lshlrev_b32_e32 v217, 4, v217
	v_xor_b32_e32 v217, v217, v110
	v_or_b32_e32 v218, s12, v108
	v_lshl_add_u32 v122, v218, 7, v217
	v_xor_b32_e32 v218, 64, v122
	v_or_b32_e32 v219, s10, v108
	v_lshl_add_u32 v109, v219, 7, v217
	v_xor_b32_e32 v219, 64, v109
	v_bfe_u32 v64, v214, 1, 3
	v_and_b32_e32 v65, 7, v104
	v_xor_b32_e32 v64, v64, v65
	v_lshlrev_b32_e32 v64, 4, v64
	v_lshl_add_u32 v64, v214, 11, v64
	v_add_u32_e32 v65, 0x10000, v64
	v_add_u32_e32 v66, 0x20000, v64
	v_add_u32_e32 v67, 0x30000, v64
	v_readlane_b32 s10, v250, 36
	v_readlane_b32 s11, v250, 37
	v_readlane_b32 s22, v249, 4
	v_readlane_b32 s23, v249, 5
	s_lshl_b32 s12, s9, 11
	s_add_u32 s10, s10, s12
	s_addc_u32 s11, s11, 0
	s_lshl_b32 s12, s8, 11
	s_add_u32 s22, s22, s12
	s_addc_u32 s23, s23, 0
	s_add_u32 m0, s0, 0x0
	s_nop 0
	global_load_lds_dwordx4 v64, s[10:11]
	s_add_u32 m0, s0, 0x1000
	s_nop 0
	global_load_lds_dwordx4 v65, s[10:11]
	s_add_u32 m0, s0, 0x2000
	s_nop 0
	global_load_lds_dwordx4 v66, s[10:11]
	s_add_u32 m0, s0, 0x3000
	s_nop 0
	global_load_lds_dwordx4 v67, s[10:11]
	s_add_u32 m0, s0, 0x9000
	s_nop 0
	global_load_lds_dwordx4 v64, s[22:23]
	s_add_u32 m0, s0, 0xa000
	s_nop 0
	global_load_lds_dwordx4 v65, s[22:23]
	s_add_u32 m0, s0, 0xb000
	s_nop 0
	global_load_lds_dwordx4 v66, s[22:23]
	s_add_u32 m0, s0, 0xc000
	s_nop 0
	global_load_lds_dwordx4 v67, s[22:23]
	s_add_u32 s10, s10, 0x80
	s_addc_u32 s11, s11, 0
	s_add_u32 s22, s22, 0x80
	s_addc_u32 s23, s23, 0
	v_mov_b64_e32 v[0:1], 0
	v_mov_b64_e32 v[2:3], 0
	v_mov_b64_e32 v[4:5], 0
	v_mov_b64_e32 v[6:7], 0
	v_mov_b64_e32 v[8:9], 0
	v_mov_b64_e32 v[10:11], 0
	v_mov_b64_e32 v[12:13], 0
	v_mov_b64_e32 v[14:15], 0
	v_mov_b64_e32 v[16:17], 0
	v_mov_b64_e32 v[18:19], 0
	v_mov_b64_e32 v[20:21], 0
	v_mov_b64_e32 v[22:23], 0
	v_mov_b64_e32 v[24:25], 0
	v_mov_b64_e32 v[26:27], 0
	v_mov_b64_e32 v[28:29], 0
	v_mov_b64_e32 v[30:31], 0
	v_mov_b64_e32 v[32:33], 0
	v_mov_b64_e32 v[34:35], 0
	v_mov_b64_e32 v[36:37], 0
	v_mov_b64_e32 v[38:39], 0
	v_mov_b64_e32 v[40:41], 0
	v_mov_b64_e32 v[42:43], 0
	v_mov_b64_e32 v[44:45], 0
	v_mov_b64_e32 v[46:47], 0
	v_mov_b64_e32 v[48:49], 0
	v_mov_b64_e32 v[50:51], 0
	v_mov_b64_e32 v[52:53], 0
	v_mov_b64_e32 v[54:55], 0
	v_mov_b64_e32 v[56:57], 0
	v_mov_b64_e32 v[58:59], 0
	v_mov_b64_e32 v[60:61], 0
	v_mov_b64_e32 v[62:63], 0
	s_mov_b32 s21, 0
	s_waitcnt vmcnt(0)
	s_barrier
	s_setprio 2

.Lg4_skip:
	ds_read_b128 v[68:71], v122 offset:18432
	ds_read_b128 v[84:87], v109 offset:55296
	ds_read_b128 v[88:91], v109 offset:57344
	ds_read_b128 v[92:95], v109 offset:59392
	ds_read_b128 v[130:133], v109 offset:61440
	ds_read_b128 v[72:75], v122 offset:20480
	ds_read_b128 v[76:79], v122 offset:22528
	ds_read_b128 v[80:83], v122 offset:24576
	s_waitcnt lgkmcnt(6)
	v_mfma_f32_16x16x32_bf16 v[12:15], v[68:71], v[84:87], v[12:15]
	ds_read_b128 v[134:137], v218 offset:18432
	ds_read_b128 v[150:153], v219 offset:55296
	s_waitcnt lgkmcnt(7)
	v_mfma_f32_16x16x32_bf16 v[32:35], v[68:71], v[88:91], v[32:35]
	ds_read_b128 v[154:157], v219 offset:57344
	ds_read_b128 v[170:173], v219 offset:59392
	s_waitcnt lgkmcnt(8)
	v_mfma_f32_16x16x32_bf16 v[52:55], v[68:71], v[92:95], v[52:55]
	ds_read_b128 v[174:177], v219 offset:61440
	ds_read_b128 v[138:141], v218 offset:20480
	s_waitcnt lgkmcnt(9)
	v_mfma_f32_16x16x32_bf16 v[56:59], v[68:71], v[130:133], v[56:59]
	ds_read_b128 v[142:145], v218 offset:22528
	s_waitcnt lgkmcnt(9)
	v_mfma_f32_16x16x32_bf16 v[36:39], v[72:75], v[84:87], v[36:39]
	v_mfma_f32_16x16x32_bf16 v[40:43], v[72:75], v[88:91], v[40:43]
	v_mfma_f32_16x16x32_bf16 v[44:47], v[72:75], v[92:95], v[44:47]
	v_mfma_f32_16x16x32_bf16 v[48:51], v[72:75], v[130:133], v[48:51]
	ds_read_b128 v[146:149], v218 offset:24576
	s_waitcnt lgkmcnt(9)
	v_mfma_f32_16x16x32_bf16 v[24:27], v[76:79], v[84:87], v[24:27]
	v_mfma_f32_16x16x32_bf16 v[20:23], v[76:79], v[88:91], v[20:23]
	v_mfma_f32_16x16x32_bf16 v[16:19], v[76:79], v[92:95], v[16:19]
	v_mfma_f32_16x16x32_bf16 v[28:31], v[76:79], v[130:133], v[28:31]
	s_waitcnt lgkmcnt(8)
	v_mfma_f32_16x16x32_bf16 v[0:3], v[80:83], v[84:87], v[0:3]
	v_mfma_f32_16x16x32_bf16 v[4:7], v[80:83], v[88:91], v[4:7]
	v_mfma_f32_16x16x32_bf16 v[8:11], v[80:83], v[92:95], v[8:11]
	v_mfma_f32_16x16x32_bf16 v[60:63], v[80:83], v[130:133], v[60:63]
	s_waitcnt lgkmcnt(6)
	v_mfma_f32_16x16x32_bf16 v[12:15], v[134:137], v[150:153], v[12:15]
	s_waitcnt lgkmcnt(5)
	v_mfma_f32_16x16x32_bf16 v[32:35], v[134:137], v[154:157], v[32:35]
	s_waitcnt lgkmcnt(4)
	v_mfma_f32_16x16x32_bf16 v[52:55], v[134:137], v[170:173], v[52:55]
	s_waitcnt lgkmcnt(3)
	v_mfma_f32_16x16x32_bf16 v[56:59], v[134:137], v[174:177], v[56:59]
	s_waitcnt lgkmcnt(2)
	v_mfma_f32_16x16x32_bf16 v[36:39], v[138:141], v[150:153], v[36:39]
	v_mfma_f32_16x16x32_bf16 v[40:43], v[138:141], v[154:157], v[40:43]
	v_mfma_f32_16x16x32_bf16 v[44:47], v[138:141], v[170:173], v[44:47]
	v_mfma_f32_16x16x32_bf16 v[48:51], v[138:141], v[174:177], v[48:51]
	s_waitcnt lgkmcnt(1)
	v_mfma_f32_16x16x32_bf16 v[24:27], v[142:145], v[150:153], v[24:27]
	v_mfma_f32_16x16x32_bf16 v[20:23], v[142:145], v[154:157], v[20:23]
	v_mfma_f32_16x16x32_bf16 v[16:19], v[142:145], v[170:173], v[16:19]
	v_mfma_f32_16x16x32_bf16 v[28:31], v[142:145], v[174:177], v[28:31]
	s_waitcnt lgkmcnt(0)
	v_mfma_f32_16x16x32_bf16 v[0:3], v[146:149], v[150:153], v[0:3]
	v_mfma_f32_16x16x32_bf16 v[4:7], v[146:149], v[154:157], v[4:7]
	v_mfma_f32_16x16x32_bf16 v[8:11], v[146:149], v[170:173], v[8:11]
	v_mfma_f32_16x16x32_bf16 v[60:63], v[146:149], v[174:177], v[60:63]
	s_waitcnt vmcnt(0)
	s_barrier
	s_add_i32 s21, s21, 1
	s_cmp_lg_u32 s21, 8
	s_cbranch_scc1 .Lg4_loop
	s_setprio 0
	v_readfirstlane_b32 s0, v104
	s_and_b32 s10, s0, 64
	s_lshr_b32 s0, s0, 1
	s_and_b32 s12, s0, 0x7fffffc0
	s_lshl_b32 s0, s8, 2
	s_add_u32 s8, s36, s0
	s_waitcnt vmcnt(6)
	v_or_b32_e32 v64, s9, v112
	s_addc_u32 s9, s37, 0
	s_lshl_b32 s10, s10, 2
	s_add_u32 s8, s8, s10
	v_add_u32_e32 v116, s12, v64
	s_addc_u32 s9, s9, 0
	v_mov_b32_e32 v115, v117
	v_lshl_add_u64 v[64:65], s[8:9], 0, v[114:115]
	v_lshlrev_b64 v[66:67], 12, v[116:117]
	v_lshl_add_u64 v[68:69], v[64:65], 0, v[66:67]
	v_or_b32_e32 v70, 0x1000, v66
	v_mov_b32_e32 v71, v67
	s_waitcnt vmcnt(5)
	v_lshl_add_u64 v[72:73], v[64:65], 0, v[70:71]
	global_load_dword v106, v[68:69], off
	global_load_dword v107, v[68:69], off offset:64
	global_load_dword v109, v[68:69], off offset:128
	global_load_dword v111, v[68:69], off offset:192
	global_load_dword v113, v[72:73], off
	global_load_dword v116, v[72:73], off offset:64
	global_load_dword v118, v[72:73], off offset:128
	global_load_dword v119, v[72:73], off offset:192
	v_or_b32_e32 v68, 0x2000, v66
	v_mov_b32_e32 v69, v67
	v_lshl_add_u64 v[72:73], v[64:65], 0, v[68:69]
	v_or_b32_e32 v74, 0x3000, v66
	v_mov_b32_e32 v75, v67
	s_waitcnt vmcnt(9)
	v_lshl_add_u64 v[76:77], v[64:65], 0, v[74:75]
	global_load_dword v120, v[72:73], off
	global_load_dword v121, v[72:73], off offset:64
	global_load_dword v122, v[72:73], off offset:128
	global_load_dword v123, v[72:73], off offset:192
	global_load_dword v124, v[76:77], off
	global_load_dword v125, v[76:77], off offset:64
	global_load_dword v126, v[76:77], off offset:128
	global_load_dword v127, v[76:77], off offset:192
	v_or_b32_e32 v72, 0x10000, v66
	v_mov_b32_e32 v73, v67
	v_lshl_add_u64 v[76:77], v[64:65], 0, v[72:73]
	v_or_b32_e32 v78, 0x11000, v66
	v_mov_b32_e32 v79, v67
	v_lshl_add_u64 v[80:81], v[64:65], 0, v[78:79]
	global_load_dword v128, v[76:77], off
	global_load_dword v129, v[76:77], off offset:64
	global_load_dword v130, v[76:77], off offset:128
	global_load_dword v131, v[76:77], off offset:192
	global_load_dword v132, v[80:81], off
	global_load_dword v133, v[80:81], off offset:64
	global_load_dword v134, v[80:81], off offset:128
	global_load_dword v135, v[80:81], off offset:192
	v_or_b32_e32 v76, 0x12000, v66
	v_mov_b32_e32 v77, v67
	v_lshl_add_u64 v[80:81], v[64:65], 0, v[76:77]
	v_or_b32_e32 v82, 0x13000, v66
	v_mov_b32_e32 v83, v67
	v_lshl_add_u64 v[84:85], v[64:65], 0, v[82:83]
	global_load_dword v136, v[80:81], off
	global_load_dword v137, v[80:81], off offset:64
	global_load_dword v138, v[80:81], off offset:128
	global_load_dword v139, v[80:81], off offset:192
	global_load_dword v140, v[84:85], off
	global_load_dword v141, v[84:85], off offset:64
	global_load_dword v142, v[84:85], off offset:128
	global_load_dword v143, v[84:85], off offset:192
	v_or_b32_e32 v80, 0x20000, v66
	v_mov_b32_e32 v81, v67
	v_lshl_add_u64 v[84:85], v[64:65], 0, v[80:81]
	v_or_b32_e32 v86, 0x21000, v66
	v_mov_b32_e32 v87, v67
	v_lshl_add_u64 v[88:89], v[64:65], 0, v[86:87]
	global_load_dword v144, v[84:85], off
	global_load_dword v145, v[84:85], off offset:64
	global_load_dword v146, v[84:85], off offset:128
	global_load_dword v147, v[84:85], off offset:192
	global_load_dword v148, v[88:89], off
	global_load_dword v149, v[88:89], off offset:64
	global_load_dword v150, v[88:89], off offset:128
	global_load_dword v151, v[88:89], off offset:192
	v_or_b32_e32 v84, 0x22000, v66
	v_mov_b32_e32 v85, v67
	v_lshl_add_u64 v[88:89], v[64:65], 0, v[84:85]
	v_or_b32_e32 v90, 0x23000, v66
	v_mov_b32_e32 v91, v67
	s_waitcnt vmcnt(40)
	v_lshl_add_u64 v[92:93], v[64:65], 0, v[90:91]
	global_load_dword v152, v[88:89], off
	global_load_dword v153, v[88:89], off offset:64
	global_load_dword v154, v[88:89], off offset:128
	global_load_dword v155, v[88:89], off offset:192
	global_load_dword v156, v[92:93], off
	global_load_dword v157, v[92:93], off offset:64
	global_load_dword v158, v[92:93], off offset:128
	global_load_dword v159, v[92:93], off offset:192
	v_or_b32_e32 v88, 0x30000, v66
	v_mov_b32_e32 v89, v67
	v_lshl_add_u64 v[92:93], v[64:65], 0, v[88:89]
	v_or_b32_e32 v94, 0x31000, v66
	v_mov_b32_e32 v95, v67
	v_lshl_add_u64 v[100:101], v[64:65], 0, v[94:95]
	global_load_dword v160, v[92:93], off
	global_load_dword v161, v[92:93], off offset:64
	global_load_dword v162, v[92:93], off offset:128
	global_load_dword v163, v[92:93], off offset:192
	global_load_dword v164, v[100:101], off
	global_load_dword v165, v[100:101], off offset:64
	global_load_dword v166, v[100:101], off offset:128
	global_load_dword v167, v[100:101], off offset:192
	v_or_b32_e32 v92, 0x32000, v66
	v_mov_b32_e32 v93, v67
	v_lshl_add_u64 v[100:101], v[64:65], 0, v[92:93]
	v_or_b32_e32 v102, 0x33000, v66
	v_mov_b32_e32 v103, v67
	v_lshl_add_u64 v[64:65], v[64:65], 0, v[102:103]
	global_load_dword v168, v[100:101], off
	global_load_dword v169, v[100:101], off offset:64
	global_load_dword v170, v[100:101], off offset:128
	s_nop 0
	global_load_dword v100, v[100:101], off offset:192
	s_nop 0
	global_load_dword v101, v[64:65], off
	global_load_dword v171, v[64:65], off offset:64
	global_load_dword v172, v[64:65], off offset:128
	global_load_dword v173, v[64:65], off offset:192
	s_add_u32 s0, s52, s0
	s_addc_u32 s9, s53, 0
	s_add_u32 s8, s0, s10
	s_addc_u32 s9, s9, 0
	v_lshl_add_u64 v[64:65], s[8:9], 0, v[114:115]
	v_lshl_add_u64 v[66:67], v[64:65], 0, v[66:67]
	s_waitcnt vmcnt(62)
	v_add_f32_e32 v12, v12, v106
	global_store_dword v[66:67], v12, off
	v_add_f32_e32 v12, v32, v107
	global_store_dword v[66:67], v12, off offset:64
	s_waitcnt vmcnt(62)
	v_add_f32_e32 v12, v52, v109
	global_store_dword v[66:67], v12, off offset:128
	v_add_f32_e32 v12, v56, v111
	global_store_dword v[66:67], v12, off offset:192
	v_lshl_add_u64 v[66:67], v[64:65], 0, v[70:71]
	s_waitcnt vmcnt(62)
	v_add_f32_e32 v12, v13, v113
	global_store_dword v[66:67], v12, off
	v_add_f32_e32 v12, v33, v116
	global_store_dword v[66:67], v12, off offset:64
	s_waitcnt vmcnt(62)
	v_add_f32_e32 v12, v53, v118
	global_store_dword v[66:67], v12, off offset:128
	v_add_f32_e32 v12, v57, v119
	global_store_dword v[66:67], v12, off offset:192
	v_lshl_add_u64 v[12:13], v[64:65], 0, v[68:69]
	s_waitcnt vmcnt(62)
	v_add_f32_e32 v14, v14, v120
	global_store_dword v[12:13], v14, off
	v_add_f32_e32 v14, v34, v121
	global_store_dword v[12:13], v14, off offset:64
	s_waitcnt vmcnt(62)
	v_add_f32_e32 v14, v54, v122
	global_store_dword v[12:13], v14, off offset:128
	v_add_f32_e32 v14, v58, v123
	global_store_dword v[12:13], v14, off offset:192
	v_lshl_add_u64 v[12:13], v[64:65], 0, v[74:75]
	s_waitcnt vmcnt(62)
	v_add_f32_e32 v14, v15, v124
	global_store_dword v[12:13], v14, off
	v_add_f32_e32 v14, v35, v125
	global_store_dword v[12:13], v14, off offset:64
	s_waitcnt vmcnt(62)
	v_add_f32_e32 v14, v55, v126
	global_store_dword v[12:13], v14, off offset:128
	v_add_f32_e32 v14, v59, v127
	global_store_dword v[12:13], v14, off offset:192
	v_lshl_add_u64 v[12:13], v[64:65], 0, v[72:73]
	s_waitcnt vmcnt(62)
	v_add_f32_e32 v14, v36, v128
	global_store_dword v[12:13], v14, off
	v_add_f32_e32 v14, v40, v129
	global_store_dword v[12:13], v14, off offset:64
	s_waitcnt vmcnt(62)
	v_add_f32_e32 v14, v44, v130
	global_store_dword v[12:13], v14, off offset:128
	v_add_f32_e32 v14, v48, v131
	global_store_dword v[12:13], v14, off offset:192
	v_lshl_add_u64 v[12:13], v[64:65], 0, v[78:79]
	s_waitcnt vmcnt(62)
	v_add_f32_e32 v14, v37, v132
	global_store_dword v[12:13], v14, off
	v_add_f32_e32 v14, v41, v133
	global_store_dword v[12:13], v14, off offset:64
	s_waitcnt vmcnt(62)
	v_add_f32_e32 v14, v45, v134
	global_store_dword v[12:13], v14, off offset:128
	v_add_f32_e32 v14, v49, v135
	global_store_dword v[12:13], v14, off offset:192
	v_lshl_add_u64 v[12:13], v[64:65], 0, v[76:77]
	s_waitcnt vmcnt(62)
	v_add_f32_e32 v14, v38, v136
	global_store_dword v[12:13], v14, off
	v_add_f32_e32 v14, v42, v137
	global_store_dword v[12:13], v14, off offset:64
	s_waitcnt vmcnt(62)
	v_add_f32_e32 v14, v46, v138
	global_store_dword v[12:13], v14, off offset:128
	v_add_f32_e32 v14, v50, v139
	global_store_dword v[12:13], v14, off offset:192
	v_lshl_add_u64 v[12:13], v[64:65], 0, v[82:83]
	s_waitcnt vmcnt(62)
	v_add_f32_e32 v14, v39, v140
	global_store_dword v[12:13], v14, off
	v_add_f32_e32 v14, v43, v141
	global_store_dword v[12:13], v14, off offset:64
	s_waitcnt vmcnt(62)
	v_add_f32_e32 v14, v47, v142
	global_store_dword v[12:13], v14, off offset:128
	v_add_f32_e32 v14, v51, v143
	global_store_dword v[12:13], v14, off offset:192
	v_lshl_add_u64 v[12:13], v[64:65], 0, v[80:81]
	s_waitcnt vmcnt(62)
	v_add_f32_e32 v14, v24, v144
	global_store_dword v[12:13], v14, off
	v_add_f32_e32 v14, v20, v145
	global_store_dword v[12:13], v14, off offset:64
	s_waitcnt vmcnt(62)
	v_add_f32_e32 v14, v16, v146
	global_store_dword v[12:13], v14, off offset:128
	v_add_f32_e32 v14, v28, v147
	global_store_dword v[12:13], v14, off offset:192
	v_lshl_add_u64 v[12:13], v[64:65], 0, v[86:87]
	s_waitcnt vmcnt(62)
	v_add_f32_e32 v14, v25, v148
	global_store_dword v[12:13], v14, off
	v_add_f32_e32 v14, v21, v149
	global_store_dword v[12:13], v14, off offset:64
	s_waitcnt vmcnt(62)
	v_add_f32_e32 v14, v17, v150
	global_store_dword v[12:13], v14, off offset:128
	v_add_f32_e32 v14, v29, v151
	global_store_dword v[12:13], v14, off offset:192
	v_lshl_add_u64 v[12:13], v[64:65], 0, v[84:85]
	s_waitcnt vmcnt(62)
	v_add_f32_e32 v14, v26, v152
	global_store_dword v[12:13], v14, off
	v_add_f32_e32 v14, v22, v153
	global_store_dword v[12:13], v14, off offset:64
	s_waitcnt vmcnt(62)
	v_add_f32_e32 v14, v18, v154
	global_store_dword v[12:13], v14, off offset:128
	v_add_f32_e32 v14, v30, v155
	global_store_dword v[12:13], v14, off offset:192
	v_lshl_add_u64 v[12:13], v[64:65], 0, v[90:91]
	s_waitcnt vmcnt(62)
	v_add_f32_e32 v14, v27, v156
	global_store_dword v[12:13], v14, off
	v_add_f32_e32 v14, v23, v157
	global_store_dword v[12:13], v14, off offset:64
	s_waitcnt vmcnt(62)
	v_add_f32_e32 v14, v19, v158
	global_store_dword v[12:13], v14, off offset:128
	v_add_f32_e32 v14, v31, v159
	global_store_dword v[12:13], v14, off offset:192
	v_lshl_add_u64 v[12:13], v[64:65], 0, v[88:89]
	s_waitcnt vmcnt(62)
	v_add_f32_e32 v0, v0, v160
	global_store_dword v[12:13], v0, off
	v_add_f32_e32 v0, v4, v161
	global_store_dword v[12:13], v0, off offset:64
	s_waitcnt vmcnt(62)
	v_add_f32_e32 v0, v8, v162
	global_store_dword v[12:13], v0, off offset:128
	v_add_f32_e32 v0, v60, v163
	global_store_dword v[12:13], v0, off offset:192
	v_lshl_add_u64 v[12:13], v[64:65], 0, v[94:95]
	s_waitcnt vmcnt(62)
	v_add_f32_e32 v0, v1, v164
	global_store_dword v[12:13], v0, off
	v_add_f32_e32 v0, v5, v165
	global_store_dword v[12:13], v0, off offset:64
	s_waitcnt vmcnt(62)
	v_add_f32_e32 v0, v9, v166
	global_store_dword v[12:13], v0, off offset:128
	v_add_f32_e32 v0, v61, v167
	global_store_dword v[12:13], v0, off offset:192
	v_lshl_add_u64 v[0:1], v[64:65], 0, v[92:93]
	s_waitcnt vmcnt(62)
	v_add_f32_e32 v2, v2, v168
	global_store_dword v[0:1], v2, off
	v_add_f32_e32 v2, v6, v169
	global_store_dword v[0:1], v2, off offset:64
	s_waitcnt vmcnt(62)
	v_add_f32_e32 v2, v10, v170
	global_store_dword v[0:1], v2, off offset:128
	v_add_f32_e32 v2, v62, v100
	global_store_dword v[0:1], v2, off offset:192
	v_lshl_add_u64 v[0:1], v[64:65], 0, v[102:103]
	s_waitcnt vmcnt(62)
	v_add_f32_e32 v2, v3, v101
	global_store_dword v[0:1], v2, off
	v_add_f32_e32 v2, v7, v171
	global_store_dword v[0:1], v2, off offset:64
	s_waitcnt vmcnt(62)
	v_add_f32_e32 v2, v11, v172
	global_store_dword v[0:1], v2, off offset:128
	v_add_f32_e32 v2, v63, v173
	global_store_dword v[0:1], v2, off offset:192
	s_branch .LBB0_892
